# top-k key staging: the eight dependent load-convert-write rounds per thread replaced by sixteen loads issued together, then eight conversions
# speedup vs baseline: 1.0067x; 1.0046x over previous
.LBB0_984:
	v_mov_b32_e32 v2, v1
	s_movk_i32 s45, 0x800
	v_cmp_gt_u32_e32 vcc, s45, v2
	v_mov_b32_e32 v4, s91
	v_mov_b32_e32 v5, s89
	v_cndmask_b32_e32 v5, v4, v5, vcc
	v_mov_b32_e32 v4, s90
	v_mov_b32_e32 v6, s88
	v_cndmask_b32_e32 v4, v4, v6, vcc
	v_lshlrev_b32_e32 v6, 5, v2
	v_and_b32_e32 v6, 0xfe00, v6
	v_lshl_or_b32 v46, s44, 2, v6
	v_lshl_add_u64 v[4:5], v[4:5], 0, v[46:47]
	v_mov_b32_e32 v53, v47
	v_lshl_add_u64 v[8:9], v[4:5], 0, v[52:53]
	global_load_dwordx4 v[80:83], v[8:9], off offset:16
	s_nop 0
	global_load_dwordx4 v[84:87], v[8:9], off
	v_add_u32_e32 v2, 0x200, v1
	s_movk_i32 s45, 0x800
	v_cmp_gt_u32_e32 vcc, s45, v2
	v_mov_b32_e32 v4, s91
	v_mov_b32_e32 v5, s89
	v_cndmask_b32_e32 v5, v4, v5, vcc
	v_mov_b32_e32 v4, s90
	v_mov_b32_e32 v6, s88
	v_cndmask_b32_e32 v4, v4, v6, vcc
	v_lshlrev_b32_e32 v6, 5, v2
	v_and_b32_e32 v6, 0xfe00, v6
	v_lshl_or_b32 v46, s44, 2, v6
	v_lshl_add_u64 v[4:5], v[4:5], 0, v[46:47]
	v_mov_b32_e32 v53, v47
	v_lshl_add_u64 v[8:9], v[4:5], 0, v[52:53]
	global_load_dwordx4 v[88:91], v[8:9], off offset:16
	s_nop 0
	global_load_dwordx4 v[92:95], v[8:9], off
	v_add_u32_e32 v2, 0x400, v1
	s_movk_i32 s45, 0x800
	v_cmp_gt_u32_e32 vcc, s45, v2
	v_mov_b32_e32 v4, s91
	v_mov_b32_e32 v5, s89
	v_cndmask_b32_e32 v5, v4, v5, vcc
	v_mov_b32_e32 v4, s90
	v_mov_b32_e32 v6, s88
	v_cndmask_b32_e32 v4, v4, v6, vcc
	v_lshlrev_b32_e32 v6, 5, v2
	v_and_b32_e32 v6, 0xfe00, v6
	v_lshl_or_b32 v46, s44, 2, v6
	v_lshl_add_u64 v[4:5], v[4:5], 0, v[46:47]
	v_mov_b32_e32 v53, v47
	v_lshl_add_u64 v[8:9], v[4:5], 0, v[52:53]
	global_load_dwordx4 v[96:99], v[8:9], off offset:16
	s_nop 0
	global_load_dwordx4 v[100:103], v[8:9], off
	v_add_u32_e32 v2, 0x600, v1
	s_movk_i32 s45, 0x800
	v_cmp_gt_u32_e32 vcc, s45, v2
	v_mov_b32_e32 v4, s91
	v_mov_b32_e32 v5, s89
	v_cndmask_b32_e32 v5, v4, v5, vcc
	v_mov_b32_e32 v4, s90
	v_mov_b32_e32 v6, s88
	v_cndmask_b32_e32 v4, v4, v6, vcc
	v_lshlrev_b32_e32 v6, 5, v2
	v_and_b32_e32 v6, 0xfe00, v6
	v_lshl_or_b32 v46, s44, 2, v6
	v_lshl_add_u64 v[4:5], v[4:5], 0, v[46:47]
	v_mov_b32_e32 v53, v47
	v_lshl_add_u64 v[8:9], v[4:5], 0, v[52:53]
	global_load_dwordx4 v[104:107], v[8:9], off offset:16
	s_nop 0
	global_load_dwordx4 v[108:111], v[8:9], off
	v_add_u32_e32 v2, 0x800, v1
	s_movk_i32 s45, 0x800
	v_cmp_gt_u32_e32 vcc, s45, v2
	v_mov_b32_e32 v4, s91
	v_mov_b32_e32 v5, s89
	v_cndmask_b32_e32 v5, v4, v5, vcc
	v_mov_b32_e32 v4, s90
	v_mov_b32_e32 v6, s88
	v_cndmask_b32_e32 v4, v4, v6, vcc
	v_lshlrev_b32_e32 v6, 5, v2
	v_and_b32_e32 v6, 0xfe00, v6
	v_lshl_or_b32 v46, s44, 2, v6
	v_lshl_add_u64 v[4:5], v[4:5], 0, v[46:47]
	v_mov_b32_e32 v53, v47
	v_lshl_add_u64 v[8:9], v[4:5], 0, v[52:53]
	global_load_dwordx4 v[148:151], v[8:9], off offset:16
	s_nop 0
	global_load_dwordx4 v[152:155], v[8:9], off
	v_add_u32_e32 v2, 0xa00, v1
	s_movk_i32 s45, 0x800
	v_cmp_gt_u32_e32 vcc, s45, v2
	v_mov_b32_e32 v4, s91
	v_mov_b32_e32 v5, s89
	v_cndmask_b32_e32 v5, v4, v5, vcc
	v_mov_b32_e32 v4, s90
	v_mov_b32_e32 v6, s88
	v_cndmask_b32_e32 v4, v4, v6, vcc
	v_lshlrev_b32_e32 v6, 5, v2
	v_and_b32_e32 v6, 0xfe00, v6
	v_lshl_or_b32 v46, s44, 2, v6
	v_lshl_add_u64 v[4:5], v[4:5], 0, v[46:47]
	v_mov_b32_e32 v53, v47
	v_lshl_add_u64 v[8:9], v[4:5], 0, v[52:53]
	global_load_dwordx4 v[156:159], v[8:9], off offset:16
	s_nop 0
	global_load_dwordx4 v[160:163], v[8:9], off
	v_add_u32_e32 v2, 0xc00, v1
	s_movk_i32 s45, 0x800
	v_cmp_gt_u32_e32 vcc, s45, v2
	v_mov_b32_e32 v4, s91
	v_mov_b32_e32 v5, s89
	v_cndmask_b32_e32 v5, v4, v5, vcc
	v_mov_b32_e32 v4, s90
	v_mov_b32_e32 v6, s88
	v_cndmask_b32_e32 v4, v4, v6, vcc
	v_lshlrev_b32_e32 v6, 5, v2
	v_and_b32_e32 v6, 0xfe00, v6
	v_lshl_or_b32 v46, s44, 2, v6
	v_lshl_add_u64 v[4:5], v[4:5], 0, v[46:47]
	v_mov_b32_e32 v53, v47
	v_lshl_add_u64 v[8:9], v[4:5], 0, v[52:53]
	global_load_dwordx4 v[164:167], v[8:9], off offset:16
	s_nop 0
	global_load_dwordx4 v[168:171], v[8:9], off
	v_add_u32_e32 v2, 0xe00, v1
	s_movk_i32 s45, 0x800
	v_cmp_gt_u32_e32 vcc, s45, v2
	v_mov_b32_e32 v4, s91
	v_mov_b32_e32 v5, s89
	v_cndmask_b32_e32 v5, v4, v5, vcc
	v_mov_b32_e32 v4, s90
	v_mov_b32_e32 v6, s88
	v_cndmask_b32_e32 v4, v4, v6, vcc
	v_lshlrev_b32_e32 v6, 5, v2
	v_and_b32_e32 v6, 0xfe00, v6
	v_lshl_or_b32 v46, s44, 2, v6
	v_lshl_add_u64 v[4:5], v[4:5], 0, v[46:47]
	v_mov_b32_e32 v53, v47
	v_lshl_add_u64 v[8:9], v[4:5], 0, v[52:53]
	global_load_dwordx4 v[172:175], v[8:9], off offset:16
	s_nop 0
	global_load_dwordx4 v[176:179], v[8:9], off
	v_mov_b32_e32 v2, v1
	s_movk_i32 s45, 0x800
	v_cmp_gt_u32_e32 vcc, s45, v2
	v_mov_b32_e32 v4, s91
	v_mov_b32_e32 v5, s89
	v_cndmask_b32_e32 v5, v4, v5, vcc
	v_mov_b32_e32 v4, s90
	v_mov_b32_e32 v6, s88
	v_cndmask_b32_e32 v4, v4, v6, vcc
	v_lshlrev_b32_e32 v6, 5, v2
	v_and_b32_e32 v6, 0xfe00, v6
	v_lshl_or_b32 v46, s44, 2, v6
	v_lshl_add_u64 v[4:5], v[4:5], 0, v[46:47]
	v_mov_b32_e32 v53, v47
	v_lshl_add_u64 v[8:9], v[4:5], 0, v[52:53]
	s_waitcnt vmcnt(14)
	v_mov_b32_e32 v4, v80
	v_mov_b32_e32 v5, v81
	v_mov_b32_e32 v6, v82
	v_mov_b32_e32 v7, v83
	v_mov_b32_e32 v8, v84
	v_mov_b32_e32 v9, v85
	v_mov_b32_e32 v10, v86
	v_mov_b32_e32 v11, v87
	v_lshrrev_b32_e32 v3, 4, v2
	s_movk_i32 s45, 0x120
	v_cvt_pk_bf16_f32 v8, v8, v9
	v_cvt_pk_bf16_f32 v9, v10, v11
	v_cvt_pk_bf16_f32 v10, v4, v5
	v_mad_u64_u32 v[4:5], s[46:47], v3, s45, v[50:51]
	s_movk_i32 s45, 0xdff
	v_cvt_pk_bf16_f32 v11, v6, v7
	ds_write_b128 v4, v[8:11]
	v_add_u32_e32 v2, 0x200, v1
	s_movk_i32 s45, 0x800
	v_cmp_gt_u32_e32 vcc, s45, v2
	v_mov_b32_e32 v4, s91
	v_mov_b32_e32 v5, s89
	v_cndmask_b32_e32 v5, v4, v5, vcc
	v_mov_b32_e32 v4, s90
	v_mov_b32_e32 v6, s88
	v_cndmask_b32_e32 v4, v4, v6, vcc
	v_lshlrev_b32_e32 v6, 5, v2
	v_and_b32_e32 v6, 0xfe00, v6
	v_lshl_or_b32 v46, s44, 2, v6
	v_lshl_add_u64 v[4:5], v[4:5], 0, v[46:47]
	v_mov_b32_e32 v53, v47
	v_lshl_add_u64 v[8:9], v[4:5], 0, v[52:53]
	s_waitcnt vmcnt(12)
	v_mov_b32_e32 v4, v88
	v_mov_b32_e32 v5, v89
	v_mov_b32_e32 v6, v90
	v_mov_b32_e32 v7, v91
	v_mov_b32_e32 v8, v92
	v_mov_b32_e32 v9, v93
	v_mov_b32_e32 v10, v94
	v_mov_b32_e32 v11, v95
	v_lshrrev_b32_e32 v3, 4, v2
	s_movk_i32 s45, 0x120
	v_cvt_pk_bf16_f32 v8, v8, v9
	v_cvt_pk_bf16_f32 v9, v10, v11
	v_cvt_pk_bf16_f32 v10, v4, v5
	v_mad_u64_u32 v[4:5], s[46:47], v3, s45, v[50:51]
	s_movk_i32 s45, 0xdff
	v_cvt_pk_bf16_f32 v11, v6, v7
	ds_write_b128 v4, v[8:11]
	v_add_u32_e32 v2, 0x400, v1
	s_movk_i32 s45, 0x800
	v_cmp_gt_u32_e32 vcc, s45, v2
	v_mov_b32_e32 v4, s91
	v_mov_b32_e32 v5, s89
	v_cndmask_b32_e32 v5, v4, v5, vcc
	v_mov_b32_e32 v4, s90
	v_mov_b32_e32 v6, s88
	v_cndmask_b32_e32 v4, v4, v6, vcc
	v_lshlrev_b32_e32 v6, 5, v2
	v_and_b32_e32 v6, 0xfe00, v6
	v_lshl_or_b32 v46, s44, 2, v6
	v_lshl_add_u64 v[4:5], v[4:5], 0, v[46:47]
	v_mov_b32_e32 v53, v47
	v_lshl_add_u64 v[8:9], v[4:5], 0, v[52:53]
	s_waitcnt vmcnt(10)
	v_mov_b32_e32 v4, v96
	v_mov_b32_e32 v5, v97
	v_mov_b32_e32 v6, v98
	v_mov_b32_e32 v7, v99
	v_mov_b32_e32 v8, v100
	v_mov_b32_e32 v9, v101
	v_mov_b32_e32 v10, v102
	v_mov_b32_e32 v11, v103
	v_lshrrev_b32_e32 v3, 4, v2
	s_movk_i32 s45, 0x120
	v_cvt_pk_bf16_f32 v8, v8, v9
	v_cvt_pk_bf16_f32 v9, v10, v11
	v_cvt_pk_bf16_f32 v10, v4, v5
	v_mad_u64_u32 v[4:5], s[46:47], v3, s45, v[50:51]
	s_movk_i32 s45, 0xdff
	v_cvt_pk_bf16_f32 v11, v6, v7
	ds_write_b128 v4, v[8:11]
	v_add_u32_e32 v2, 0x600, v1
	s_movk_i32 s45, 0x800
	v_cmp_gt_u32_e32 vcc, s45, v2
	v_mov_b32_e32 v4, s91
	v_mov_b32_e32 v5, s89
	v_cndmask_b32_e32 v5, v4, v5, vcc
	v_mov_b32_e32 v4, s90
	v_mov_b32_e32 v6, s88
	v_cndmask_b32_e32 v4, v4, v6, vcc
	v_lshlrev_b32_e32 v6, 5, v2
	v_and_b32_e32 v6, 0xfe00, v6
	v_lshl_or_b32 v46, s44, 2, v6
	v_lshl_add_u64 v[4:5], v[4:5], 0, v[46:47]
	v_mov_b32_e32 v53, v47
	v_lshl_add_u64 v[8:9], v[4:5], 0, v[52:53]
	s_waitcnt vmcnt(8)
	v_mov_b32_e32 v4, v104
	v_mov_b32_e32 v5, v105
	v_mov_b32_e32 v6, v106
	v_mov_b32_e32 v7, v107
	v_mov_b32_e32 v8, v108
	v_mov_b32_e32 v9, v109
	v_mov_b32_e32 v10, v110
	v_mov_b32_e32 v11, v111
	v_lshrrev_b32_e32 v3, 4, v2
	s_movk_i32 s45, 0x120
	v_cvt_pk_bf16_f32 v8, v8, v9
	v_cvt_pk_bf16_f32 v9, v10, v11
	v_cvt_pk_bf16_f32 v10, v4, v5
	v_mad_u64_u32 v[4:5], s[46:47], v3, s45, v[50:51]
	s_movk_i32 s45, 0xdff
	v_cvt_pk_bf16_f32 v11, v6, v7
	ds_write_b128 v4, v[8:11]
	v_add_u32_e32 v2, 0x800, v1
	s_movk_i32 s45, 0x800
	v_cmp_gt_u32_e32 vcc, s45, v2
	v_mov_b32_e32 v4, s91
	v_mov_b32_e32 v5, s89
	v_cndmask_b32_e32 v5, v4, v5, vcc
	v_mov_b32_e32 v4, s90
	v_mov_b32_e32 v6, s88
	v_cndmask_b32_e32 v4, v4, v6, vcc
	v_lshlrev_b32_e32 v6, 5, v2
	v_and_b32_e32 v6, 0xfe00, v6
	v_lshl_or_b32 v46, s44, 2, v6
	v_lshl_add_u64 v[4:5], v[4:5], 0, v[46:47]
	v_mov_b32_e32 v53, v47
	v_lshl_add_u64 v[8:9], v[4:5], 0, v[52:53]
	s_waitcnt vmcnt(6)
	v_mov_b32_e32 v4, v148
	v_mov_b32_e32 v5, v149
	v_mov_b32_e32 v6, v150
	v_mov_b32_e32 v7, v151
	v_mov_b32_e32 v8, v152
	v_mov_b32_e32 v9, v153
	v_mov_b32_e32 v10, v154
	v_mov_b32_e32 v11, v155
	v_lshrrev_b32_e32 v3, 4, v2
	s_movk_i32 s45, 0x120
	v_cvt_pk_bf16_f32 v8, v8, v9
	v_cvt_pk_bf16_f32 v9, v10, v11
	v_cvt_pk_bf16_f32 v10, v4, v5
	v_mad_u64_u32 v[4:5], s[46:47], v3, s45, v[50:51]
	s_movk_i32 s45, 0xdff
	v_cvt_pk_bf16_f32 v11, v6, v7
	ds_write_b128 v4, v[8:11]
	v_add_u32_e32 v2, 0xa00, v1
	s_movk_i32 s45, 0x800
	v_cmp_gt_u32_e32 vcc, s45, v2
	v_mov_b32_e32 v4, s91
	v_mov_b32_e32 v5, s89
	v_cndmask_b32_e32 v5, v4, v5, vcc
	v_mov_b32_e32 v4, s90
	v_mov_b32_e32 v6, s88
	v_cndmask_b32_e32 v4, v4, v6, vcc
	v_lshlrev_b32_e32 v6, 5, v2
	v_and_b32_e32 v6, 0xfe00, v6
	v_lshl_or_b32 v46, s44, 2, v6
	v_lshl_add_u64 v[4:5], v[4:5], 0, v[46:47]
	v_mov_b32_e32 v53, v47
	v_lshl_add_u64 v[8:9], v[4:5], 0, v[52:53]
	s_waitcnt vmcnt(4)
	v_mov_b32_e32 v4, v156
	v_mov_b32_e32 v5, v157
	v_mov_b32_e32 v6, v158
	v_mov_b32_e32 v7, v159
	v_mov_b32_e32 v8, v160
	v_mov_b32_e32 v9, v161
	v_mov_b32_e32 v10, v162
	v_mov_b32_e32 v11, v163
	v_lshrrev_b32_e32 v3, 4, v2
	s_movk_i32 s45, 0x120
	v_cvt_pk_bf16_f32 v8, v8, v9
	v_cvt_pk_bf16_f32 v9, v10, v11
	v_cvt_pk_bf16_f32 v10, v4, v5
	v_mad_u64_u32 v[4:5], s[46:47], v3, s45, v[50:51]
	s_movk_i32 s45, 0xdff
	v_cvt_pk_bf16_f32 v11, v6, v7
	ds_write_b128 v4, v[8:11]
	v_add_u32_e32 v2, 0xc00, v1
	s_movk_i32 s45, 0x800
	v_cmp_gt_u32_e32 vcc, s45, v2
	v_mov_b32_e32 v4, s91
	v_mov_b32_e32 v5, s89
	v_cndmask_b32_e32 v5, v4, v5, vcc
	v_mov_b32_e32 v4, s90
	v_mov_b32_e32 v6, s88
	v_cndmask_b32_e32 v4, v4, v6, vcc
	v_lshlrev_b32_e32 v6, 5, v2
	v_and_b32_e32 v6, 0xfe00, v6
	v_lshl_or_b32 v46, s44, 2, v6
	v_lshl_add_u64 v[4:5], v[4:5], 0, v[46:47]
	v_mov_b32_e32 v53, v47
	v_lshl_add_u64 v[8:9], v[4:5], 0, v[52:53]
	s_waitcnt vmcnt(2)
	v_mov_b32_e32 v4, v164
	v_mov_b32_e32 v5, v165
	v_mov_b32_e32 v6, v166
	v_mov_b32_e32 v7, v167
	v_mov_b32_e32 v8, v168
	v_mov_b32_e32 v9, v169
	v_mov_b32_e32 v10, v170
	v_mov_b32_e32 v11, v171
	v_lshrrev_b32_e32 v3, 4, v2
	s_movk_i32 s45, 0x120
	v_cvt_pk_bf16_f32 v8, v8, v9
	v_cvt_pk_bf16_f32 v9, v10, v11
	v_cvt_pk_bf16_f32 v10, v4, v5
	v_mad_u64_u32 v[4:5], s[46:47], v3, s45, v[50:51]
	s_movk_i32 s45, 0xdff
	v_cvt_pk_bf16_f32 v11, v6, v7
	ds_write_b128 v4, v[8:11]
	v_add_u32_e32 v2, 0xe00, v1
	s_movk_i32 s45, 0x800
	v_cmp_gt_u32_e32 vcc, s45, v2
	v_mov_b32_e32 v4, s91
	v_mov_b32_e32 v5, s89
	v_cndmask_b32_e32 v5, v4, v5, vcc
	v_mov_b32_e32 v4, s90
	v_mov_b32_e32 v6, s88
	v_cndmask_b32_e32 v4, v4, v6, vcc
	v_lshlrev_b32_e32 v6, 5, v2
	v_and_b32_e32 v6, 0xfe00, v6
	v_lshl_or_b32 v46, s44, 2, v6
	v_lshl_add_u64 v[4:5], v[4:5], 0, v[46:47]
	v_mov_b32_e32 v53, v47
	v_lshl_add_u64 v[8:9], v[4:5], 0, v[52:53]
	s_waitcnt vmcnt(0)
	v_mov_b32_e32 v4, v172
	v_mov_b32_e32 v5, v173
	v_mov_b32_e32 v6, v174
	v_mov_b32_e32 v7, v175
	v_mov_b32_e32 v8, v176
	v_mov_b32_e32 v9, v177
	v_mov_b32_e32 v10, v178
	v_mov_b32_e32 v11, v179
	v_lshrrev_b32_e32 v3, 4, v2
	s_movk_i32 s45, 0x120
	v_cvt_pk_bf16_f32 v8, v8, v9
	v_cvt_pk_bf16_f32 v9, v10, v11
	v_cvt_pk_bf16_f32 v10, v4, v5
	v_mad_u64_u32 v[4:5], s[46:47], v3, s45, v[50:51]
	s_movk_i32 s45, 0xdff
	v_cvt_pk_bf16_f32 v11, v6, v7
	ds_write_b128 v4, v[8:11]

.LBB0_2017:
	v_mov_b32_e32 v2, v51
	s_movk_i32 s45, 0x800
	v_cmp_gt_u32_e32 vcc, s45, v2
	v_mov_b32_e32 v4, s91
	v_mov_b32_e32 v5, s89
	v_cndmask_b32_e32 v5, v4, v5, vcc
	v_mov_b32_e32 v4, s90
	v_mov_b32_e32 v6, s88
	v_cndmask_b32_e32 v4, v4, v6, vcc
	v_lshlrev_b32_e32 v6, 5, v2
	v_and_b32_e32 v6, 0xfe00, v6
	v_lshl_or_b32 v46, s44, 2, v6
	v_lshl_add_u64 v[4:5], v[4:5], 0, v[46:47]
	v_mov_b32_e32 v53, v47
	v_lshl_add_u64 v[4:5], v[4:5], 0, v[52:53]
	s_mov_b64 s[46:47], 0x80000
	s_mov_b32 s45, 0x80000
	v_lshl_add_u64 v[8:9], v[4:5], 0, s[46:47]
	v_add_co_u32_e32 v4, vcc, s45, v4
	v_lshrrev_b32_e32 v3, 4, v2
	s_nop 0
	v_addc_co_u32_e32 v5, vcc, 0, v5, vcc
	global_load_dwordx4 v[80:83], v[4:5], off
	s_nop 0
	global_load_dwordx4 v[84:87], v[8:9], off offset:16
	v_add_u32_e32 v2, 0x200, v51
	s_movk_i32 s45, 0x800
	v_cmp_gt_u32_e32 vcc, s45, v2
	v_mov_b32_e32 v4, s91
	v_mov_b32_e32 v5, s89
	v_cndmask_b32_e32 v5, v4, v5, vcc
	v_mov_b32_e32 v4, s90
	v_mov_b32_e32 v6, s88
	v_cndmask_b32_e32 v4, v4, v6, vcc
	v_lshlrev_b32_e32 v6, 5, v2
	v_and_b32_e32 v6, 0xfe00, v6
	v_lshl_or_b32 v46, s44, 2, v6
	v_lshl_add_u64 v[4:5], v[4:5], 0, v[46:47]
	v_mov_b32_e32 v53, v47
	v_lshl_add_u64 v[4:5], v[4:5], 0, v[52:53]
	s_mov_b64 s[46:47], 0x80000
	s_mov_b32 s45, 0x80000
	v_lshl_add_u64 v[8:9], v[4:5], 0, s[46:47]
	v_add_co_u32_e32 v4, vcc, s45, v4
	v_lshrrev_b32_e32 v3, 4, v2
	s_nop 0
	v_addc_co_u32_e32 v5, vcc, 0, v5, vcc
	global_load_dwordx4 v[88:91], v[4:5], off
	s_nop 0
	global_load_dwordx4 v[92:95], v[8:9], off offset:16
	v_add_u32_e32 v2, 0x400, v51
	s_movk_i32 s45, 0x800
	v_cmp_gt_u32_e32 vcc, s45, v2
	v_mov_b32_e32 v4, s91
	v_mov_b32_e32 v5, s89
	v_cndmask_b32_e32 v5, v4, v5, vcc
	v_mov_b32_e32 v4, s90
	v_mov_b32_e32 v6, s88
	v_cndmask_b32_e32 v4, v4, v6, vcc
	v_lshlrev_b32_e32 v6, 5, v2
	v_and_b32_e32 v6, 0xfe00, v6
	v_lshl_or_b32 v46, s44, 2, v6
	v_lshl_add_u64 v[4:5], v[4:5], 0, v[46:47]
	v_mov_b32_e32 v53, v47
	v_lshl_add_u64 v[4:5], v[4:5], 0, v[52:53]
	s_mov_b64 s[46:47], 0x80000
	s_mov_b32 s45, 0x80000
	v_lshl_add_u64 v[8:9], v[4:5], 0, s[46:47]
	v_add_co_u32_e32 v4, vcc, s45, v4
	v_lshrrev_b32_e32 v3, 4, v2
	s_nop 0
	v_addc_co_u32_e32 v5, vcc, 0, v5, vcc
	global_load_dwordx4 v[96:99], v[4:5], off
	s_nop 0
	global_load_dwordx4 v[100:103], v[8:9], off offset:16
	v_add_u32_e32 v2, 0x600, v51
	s_movk_i32 s45, 0x800
	v_cmp_gt_u32_e32 vcc, s45, v2
	v_mov_b32_e32 v4, s91
	v_mov_b32_e32 v5, s89
	v_cndmask_b32_e32 v5, v4, v5, vcc
	v_mov_b32_e32 v4, s90
	v_mov_b32_e32 v6, s88
	v_cndmask_b32_e32 v4, v4, v6, vcc
	v_lshlrev_b32_e32 v6, 5, v2
	v_and_b32_e32 v6, 0xfe00, v6
	v_lshl_or_b32 v46, s44, 2, v6
	v_lshl_add_u64 v[4:5], v[4:5], 0, v[46:47]
	v_mov_b32_e32 v53, v47
	v_lshl_add_u64 v[4:5], v[4:5], 0, v[52:53]
	s_mov_b64 s[46:47], 0x80000
	s_mov_b32 s45, 0x80000
	v_lshl_add_u64 v[8:9], v[4:5], 0, s[46:47]
	v_add_co_u32_e32 v4, vcc, s45, v4
	v_lshrrev_b32_e32 v3, 4, v2
	s_nop 0
	v_addc_co_u32_e32 v5, vcc, 0, v5, vcc
	global_load_dwordx4 v[104:107], v[4:5], off
	s_nop 0
	global_load_dwordx4 v[108:111], v[8:9], off offset:16
	v_add_u32_e32 v2, 0x800, v51
	s_movk_i32 s45, 0x800
	v_cmp_gt_u32_e32 vcc, s45, v2
	v_mov_b32_e32 v4, s91
	v_mov_b32_e32 v5, s89
	v_cndmask_b32_e32 v5, v4, v5, vcc
	v_mov_b32_e32 v4, s90
	v_mov_b32_e32 v6, s88
	v_cndmask_b32_e32 v4, v4, v6, vcc
	v_lshlrev_b32_e32 v6, 5, v2
	v_and_b32_e32 v6, 0xfe00, v6
	v_lshl_or_b32 v46, s44, 2, v6
	v_lshl_add_u64 v[4:5], v[4:5], 0, v[46:47]
	v_mov_b32_e32 v53, v47
	v_lshl_add_u64 v[4:5], v[4:5], 0, v[52:53]
	s_mov_b64 s[46:47], 0x80000
	s_mov_b32 s45, 0x80000
	v_lshl_add_u64 v[8:9], v[4:5], 0, s[46:47]
	v_add_co_u32_e32 v4, vcc, s45, v4
	v_lshrrev_b32_e32 v3, 4, v2
	s_nop 0
	v_addc_co_u32_e32 v5, vcc, 0, v5, vcc
	global_load_dwordx4 v[148:151], v[4:5], off
	s_nop 0
	global_load_dwordx4 v[152:155], v[8:9], off offset:16
	v_add_u32_e32 v2, 0xa00, v51
	s_movk_i32 s45, 0x800
	v_cmp_gt_u32_e32 vcc, s45, v2
	v_mov_b32_e32 v4, s91
	v_mov_b32_e32 v5, s89
	v_cndmask_b32_e32 v5, v4, v5, vcc
	v_mov_b32_e32 v4, s90
	v_mov_b32_e32 v6, s88
	v_cndmask_b32_e32 v4, v4, v6, vcc
	v_lshlrev_b32_e32 v6, 5, v2
	v_and_b32_e32 v6, 0xfe00, v6
	v_lshl_or_b32 v46, s44, 2, v6
	v_lshl_add_u64 v[4:5], v[4:5], 0, v[46:47]
	v_mov_b32_e32 v53, v47
	v_lshl_add_u64 v[4:5], v[4:5], 0, v[52:53]
	s_mov_b64 s[46:47], 0x80000
	s_mov_b32 s45, 0x80000
	v_lshl_add_u64 v[8:9], v[4:5], 0, s[46:47]
	v_add_co_u32_e32 v4, vcc, s45, v4
	v_lshrrev_b32_e32 v3, 4, v2
	s_nop 0
	v_addc_co_u32_e32 v5, vcc, 0, v5, vcc
	global_load_dwordx4 v[156:159], v[4:5], off
	s_nop 0
	global_load_dwordx4 v[160:163], v[8:9], off offset:16
	v_add_u32_e32 v2, 0xc00, v51
	s_movk_i32 s45, 0x800
	v_cmp_gt_u32_e32 vcc, s45, v2
	v_mov_b32_e32 v4, s91
	v_mov_b32_e32 v5, s89
	v_cndmask_b32_e32 v5, v4, v5, vcc
	v_mov_b32_e32 v4, s90
	v_mov_b32_e32 v6, s88
	v_cndmask_b32_e32 v4, v4, v6, vcc
	v_lshlrev_b32_e32 v6, 5, v2
	v_and_b32_e32 v6, 0xfe00, v6
	v_lshl_or_b32 v46, s44, 2, v6
	v_lshl_add_u64 v[4:5], v[4:5], 0, v[46:47]
	v_mov_b32_e32 v53, v47
	v_lshl_add_u64 v[4:5], v[4:5], 0, v[52:53]
	s_mov_b64 s[46:47], 0x80000
	s_mov_b32 s45, 0x80000
	v_lshl_add_u64 v[8:9], v[4:5], 0, s[46:47]
	v_add_co_u32_e32 v4, vcc, s45, v4
	v_lshrrev_b32_e32 v3, 4, v2
	s_nop 0
	v_addc_co_u32_e32 v5, vcc, 0, v5, vcc
	global_load_dwordx4 v[164:167], v[4:5], off
	s_nop 0
	global_load_dwordx4 v[168:171], v[8:9], off offset:16
	v_add_u32_e32 v2, 0xe00, v51
	s_movk_i32 s45, 0x800
	v_cmp_gt_u32_e32 vcc, s45, v2
	v_mov_b32_e32 v4, s91
	v_mov_b32_e32 v5, s89
	v_cndmask_b32_e32 v5, v4, v5, vcc
	v_mov_b32_e32 v4, s90
	v_mov_b32_e32 v6, s88
	v_cndmask_b32_e32 v4, v4, v6, vcc
	v_lshlrev_b32_e32 v6, 5, v2
	v_and_b32_e32 v6, 0xfe00, v6
	v_lshl_or_b32 v46, s44, 2, v6
	v_lshl_add_u64 v[4:5], v[4:5], 0, v[46:47]
	v_mov_b32_e32 v53, v47
	v_lshl_add_u64 v[4:5], v[4:5], 0, v[52:53]
	s_mov_b64 s[46:47], 0x80000
	s_mov_b32 s45, 0x80000
	v_lshl_add_u64 v[8:9], v[4:5], 0, s[46:47]
	v_add_co_u32_e32 v4, vcc, s45, v4
	v_lshrrev_b32_e32 v3, 4, v2
	s_nop 0
	v_addc_co_u32_e32 v5, vcc, 0, v5, vcc
	global_load_dwordx4 v[172:175], v[4:5], off
	s_nop 0
	global_load_dwordx4 v[176:179], v[8:9], off offset:16
	v_mov_b32_e32 v2, v51
	s_movk_i32 s45, 0x800
	v_cmp_gt_u32_e32 vcc, s45, v2
	v_mov_b32_e32 v4, s91
	v_mov_b32_e32 v5, s89
	v_cndmask_b32_e32 v5, v4, v5, vcc
	v_mov_b32_e32 v4, s90
	v_mov_b32_e32 v6, s88
	v_cndmask_b32_e32 v4, v4, v6, vcc
	v_lshlrev_b32_e32 v6, 5, v2
	v_and_b32_e32 v6, 0xfe00, v6
	v_lshl_or_b32 v46, s44, 2, v6
	v_lshl_add_u64 v[4:5], v[4:5], 0, v[46:47]
	v_mov_b32_e32 v53, v47
	v_lshl_add_u64 v[4:5], v[4:5], 0, v[52:53]
	s_mov_b64 s[46:47], 0x80000
	s_mov_b32 s45, 0x80000
	v_lshl_add_u64 v[8:9], v[4:5], 0, s[46:47]
	v_add_co_u32_e32 v4, vcc, s45, v4
	v_lshrrev_b32_e32 v3, 4, v2
	s_nop 0
	v_addc_co_u32_e32 v5, vcc, 0, v5, vcc
	s_waitcnt vmcnt(14)
	v_mov_b32_e32 v4, v80
	v_mov_b32_e32 v5, v81
	v_mov_b32_e32 v6, v82
	v_mov_b32_e32 v7, v83
	v_mov_b32_e32 v8, v84
	v_mov_b32_e32 v9, v85
	v_mov_b32_e32 v10, v86
	v_mov_b32_e32 v11, v87
	s_movk_i32 s45, 0x120
	v_cvt_pk_bf16_f32 v4, v4, v5
	v_cvt_pk_bf16_f32 v5, v6, v7
	v_cvt_pk_bf16_f32 v6, v8, v9
	v_mad_u64_u32 v[8:9], s[46:47], v3, s45, v[50:51]
	s_movk_i32 s45, 0xdff
	v_cvt_pk_bf16_f32 v7, v10, v11
	ds_write_b128 v8, v[4:7]
	v_add_u32_e32 v2, 0x200, v51
	s_movk_i32 s45, 0x800
	v_cmp_gt_u32_e32 vcc, s45, v2
	v_mov_b32_e32 v4, s91
	v_mov_b32_e32 v5, s89
	v_cndmask_b32_e32 v5, v4, v5, vcc
	v_mov_b32_e32 v4, s90
	v_mov_b32_e32 v6, s88
	v_cndmask_b32_e32 v4, v4, v6, vcc
	v_lshlrev_b32_e32 v6, 5, v2
	v_and_b32_e32 v6, 0xfe00, v6
	v_lshl_or_b32 v46, s44, 2, v6
	v_lshl_add_u64 v[4:5], v[4:5], 0, v[46:47]
	v_mov_b32_e32 v53, v47
	v_lshl_add_u64 v[4:5], v[4:5], 0, v[52:53]
	s_mov_b64 s[46:47], 0x80000
	s_mov_b32 s45, 0x80000
	v_lshl_add_u64 v[8:9], v[4:5], 0, s[46:47]
	v_add_co_u32_e32 v4, vcc, s45, v4
	v_lshrrev_b32_e32 v3, 4, v2
	s_nop 0
	v_addc_co_u32_e32 v5, vcc, 0, v5, vcc
	s_waitcnt vmcnt(12)
	v_mov_b32_e32 v4, v88
	v_mov_b32_e32 v5, v89
	v_mov_b32_e32 v6, v90
	v_mov_b32_e32 v7, v91
	v_mov_b32_e32 v8, v92
	v_mov_b32_e32 v9, v93
	v_mov_b32_e32 v10, v94
	v_mov_b32_e32 v11, v95
	s_movk_i32 s45, 0x120
	v_cvt_pk_bf16_f32 v4, v4, v5
	v_cvt_pk_bf16_f32 v5, v6, v7
	v_cvt_pk_bf16_f32 v6, v8, v9
	v_mad_u64_u32 v[8:9], s[46:47], v3, s45, v[50:51]
	s_movk_i32 s45, 0xdff
	v_cvt_pk_bf16_f32 v7, v10, v11
	ds_write_b128 v8, v[4:7]
	v_add_u32_e32 v2, 0x400, v51
	s_movk_i32 s45, 0x800
	v_cmp_gt_u32_e32 vcc, s45, v2
	v_mov_b32_e32 v4, s91
	v_mov_b32_e32 v5, s89
	v_cndmask_b32_e32 v5, v4, v5, vcc
	v_mov_b32_e32 v4, s90
	v_mov_b32_e32 v6, s88
	v_cndmask_b32_e32 v4, v4, v6, vcc
	v_lshlrev_b32_e32 v6, 5, v2
	v_and_b32_e32 v6, 0xfe00, v6
	v_lshl_or_b32 v46, s44, 2, v6
	v_lshl_add_u64 v[4:5], v[4:5], 0, v[46:47]
	v_mov_b32_e32 v53, v47
	v_lshl_add_u64 v[4:5], v[4:5], 0, v[52:53]
	s_mov_b64 s[46:47], 0x80000
	s_mov_b32 s45, 0x80000
	v_lshl_add_u64 v[8:9], v[4:5], 0, s[46:47]
	v_add_co_u32_e32 v4, vcc, s45, v4
	v_lshrrev_b32_e32 v3, 4, v2
	s_nop 0
	v_addc_co_u32_e32 v5, vcc, 0, v5, vcc
	s_waitcnt vmcnt(10)
	v_mov_b32_e32 v4, v96
	v_mov_b32_e32 v5, v97
	v_mov_b32_e32 v6, v98
	v_mov_b32_e32 v7, v99
	v_mov_b32_e32 v8, v100
	v_mov_b32_e32 v9, v101
	v_mov_b32_e32 v10, v102
	v_mov_b32_e32 v11, v103
	s_movk_i32 s45, 0x120
	v_cvt_pk_bf16_f32 v4, v4, v5
	v_cvt_pk_bf16_f32 v5, v6, v7
	v_cvt_pk_bf16_f32 v6, v8, v9
	v_mad_u64_u32 v[8:9], s[46:47], v3, s45, v[50:51]
	s_movk_i32 s45, 0xdff
	v_cvt_pk_bf16_f32 v7, v10, v11
	ds_write_b128 v8, v[4:7]
	v_add_u32_e32 v2, 0x600, v51
	s_movk_i32 s45, 0x800
	v_cmp_gt_u32_e32 vcc, s45, v2
	v_mov_b32_e32 v4, s91
	v_mov_b32_e32 v5, s89
	v_cndmask_b32_e32 v5, v4, v5, vcc
	v_mov_b32_e32 v4, s90
	v_mov_b32_e32 v6, s88
	v_cndmask_b32_e32 v4, v4, v6, vcc
	v_lshlrev_b32_e32 v6, 5, v2
	v_and_b32_e32 v6, 0xfe00, v6
	v_lshl_or_b32 v46, s44, 2, v6
	v_lshl_add_u64 v[4:5], v[4:5], 0, v[46:47]
	v_mov_b32_e32 v53, v47
	v_lshl_add_u64 v[4:5], v[4:5], 0, v[52:53]
	s_mov_b64 s[46:47], 0x80000
	s_mov_b32 s45, 0x80000
	v_lshl_add_u64 v[8:9], v[4:5], 0, s[46:47]
	v_add_co_u32_e32 v4, vcc, s45, v4
	v_lshrrev_b32_e32 v3, 4, v2
	s_nop 0
	v_addc_co_u32_e32 v5, vcc, 0, v5, vcc
	s_waitcnt vmcnt(8)
	v_mov_b32_e32 v4, v104
	v_mov_b32_e32 v5, v105
	v_mov_b32_e32 v6, v106
	v_mov_b32_e32 v7, v107
	v_mov_b32_e32 v8, v108
	v_mov_b32_e32 v9, v109
	v_mov_b32_e32 v10, v110
	v_mov_b32_e32 v11, v111
	s_movk_i32 s45, 0x120
	v_cvt_pk_bf16_f32 v4, v4, v5
	v_cvt_pk_bf16_f32 v5, v6, v7
	v_cvt_pk_bf16_f32 v6, v8, v9
	v_mad_u64_u32 v[8:9], s[46:47], v3, s45, v[50:51]
	s_movk_i32 s45, 0xdff
	v_cvt_pk_bf16_f32 v7, v10, v11
	ds_write_b128 v8, v[4:7]
	v_add_u32_e32 v2, 0x800, v51
	s_movk_i32 s45, 0x800
	v_cmp_gt_u32_e32 vcc, s45, v2
	v_mov_b32_e32 v4, s91
	v_mov_b32_e32 v5, s89
	v_cndmask_b32_e32 v5, v4, v5, vcc
	v_mov_b32_e32 v4, s90
	v_mov_b32_e32 v6, s88
	v_cndmask_b32_e32 v4, v4, v6, vcc
	v_lshlrev_b32_e32 v6, 5, v2
	v_and_b32_e32 v6, 0xfe00, v6
	v_lshl_or_b32 v46, s44, 2, v6
	v_lshl_add_u64 v[4:5], v[4:5], 0, v[46:47]
	v_mov_b32_e32 v53, v47
	v_lshl_add_u64 v[4:5], v[4:5], 0, v[52:53]
	s_mov_b64 s[46:47], 0x80000
	s_mov_b32 s45, 0x80000
	v_lshl_add_u64 v[8:9], v[4:5], 0, s[46:47]
	v_add_co_u32_e32 v4, vcc, s45, v4
	v_lshrrev_b32_e32 v3, 4, v2
	s_nop 0
	v_addc_co_u32_e32 v5, vcc, 0, v5, vcc
	s_waitcnt vmcnt(6)
	v_mov_b32_e32 v4, v148
	v_mov_b32_e32 v5, v149
	v_mov_b32_e32 v6, v150
	v_mov_b32_e32 v7, v151
	v_mov_b32_e32 v8, v152
	v_mov_b32_e32 v9, v153
	v_mov_b32_e32 v10, v154
	v_mov_b32_e32 v11, v155
	s_movk_i32 s45, 0x120
	v_cvt_pk_bf16_f32 v4, v4, v5
	v_cvt_pk_bf16_f32 v5, v6, v7
	v_cvt_pk_bf16_f32 v6, v8, v9
	v_mad_u64_u32 v[8:9], s[46:47], v3, s45, v[50:51]
	s_movk_i32 s45, 0xdff
	v_cvt_pk_bf16_f32 v7, v10, v11
	ds_write_b128 v8, v[4:7]
	v_add_u32_e32 v2, 0xa00, v51
	s_movk_i32 s45, 0x800
	v_cmp_gt_u32_e32 vcc, s45, v2
	v_mov_b32_e32 v4, s91
	v_mov_b32_e32 v5, s89
	v_cndmask_b32_e32 v5, v4, v5, vcc
	v_mov_b32_e32 v4, s90
	v_mov_b32_e32 v6, s88
	v_cndmask_b32_e32 v4, v4, v6, vcc
	v_lshlrev_b32_e32 v6, 5, v2
	v_and_b32_e32 v6, 0xfe00, v6
	v_lshl_or_b32 v46, s44, 2, v6
	v_lshl_add_u64 v[4:5], v[4:5], 0, v[46:47]
	v_mov_b32_e32 v53, v47
	v_lshl_add_u64 v[4:5], v[4:5], 0, v[52:53]
	s_mov_b64 s[46:47], 0x80000
	s_mov_b32 s45, 0x80000
	v_lshl_add_u64 v[8:9], v[4:5], 0, s[46:47]
	v_add_co_u32_e32 v4, vcc, s45, v4
	v_lshrrev_b32_e32 v3, 4, v2
	s_nop 0
	v_addc_co_u32_e32 v5, vcc, 0, v5, vcc
	s_waitcnt vmcnt(4)
	v_mov_b32_e32 v4, v156
	v_mov_b32_e32 v5, v157
	v_mov_b32_e32 v6, v158
	v_mov_b32_e32 v7, v159
	v_mov_b32_e32 v8, v160
	v_mov_b32_e32 v9, v161
	v_mov_b32_e32 v10, v162
	v_mov_b32_e32 v11, v163
	s_movk_i32 s45, 0x120
	v_cvt_pk_bf16_f32 v4, v4, v5
	v_cvt_pk_bf16_f32 v5, v6, v7
	v_cvt_pk_bf16_f32 v6, v8, v9
	v_mad_u64_u32 v[8:9], s[46:47], v3, s45, v[50:51]
	s_movk_i32 s45, 0xdff
	v_cvt_pk_bf16_f32 v7, v10, v11
	ds_write_b128 v8, v[4:7]
	v_add_u32_e32 v2, 0xc00, v51
	s_movk_i32 s45, 0x800
	v_cmp_gt_u32_e32 vcc, s45, v2
	v_mov_b32_e32 v4, s91
	v_mov_b32_e32 v5, s89
	v_cndmask_b32_e32 v5, v4, v5, vcc
	v_mov_b32_e32 v4, s90
	v_mov_b32_e32 v6, s88
	v_cndmask_b32_e32 v4, v4, v6, vcc
	v_lshlrev_b32_e32 v6, 5, v2
	v_and_b32_e32 v6, 0xfe00, v6
	v_lshl_or_b32 v46, s44, 2, v6
	v_lshl_add_u64 v[4:5], v[4:5], 0, v[46:47]
	v_mov_b32_e32 v53, v47
	v_lshl_add_u64 v[4:5], v[4:5], 0, v[52:53]
	s_mov_b64 s[46:47], 0x80000
	s_mov_b32 s45, 0x80000
	v_lshl_add_u64 v[8:9], v[4:5], 0, s[46:47]
	v_add_co_u32_e32 v4, vcc, s45, v4
	v_lshrrev_b32_e32 v3, 4, v2
	s_nop 0
	v_addc_co_u32_e32 v5, vcc, 0, v5, vcc
	s_waitcnt vmcnt(2)
	v_mov_b32_e32 v4, v164
	v_mov_b32_e32 v5, v165
	v_mov_b32_e32 v6, v166
	v_mov_b32_e32 v7, v167
	v_mov_b32_e32 v8, v168
	v_mov_b32_e32 v9, v169
	v_mov_b32_e32 v10, v170
	v_mov_b32_e32 v11, v171
	s_movk_i32 s45, 0x120
	v_cvt_pk_bf16_f32 v4, v4, v5
	v_cvt_pk_bf16_f32 v5, v6, v7
	v_cvt_pk_bf16_f32 v6, v8, v9
	v_mad_u64_u32 v[8:9], s[46:47], v3, s45, v[50:51]
	s_movk_i32 s45, 0xdff
	v_cvt_pk_bf16_f32 v7, v10, v11
	ds_write_b128 v8, v[4:7]
	v_add_u32_e32 v2, 0xe00, v51
	s_movk_i32 s45, 0x800
	v_cmp_gt_u32_e32 vcc, s45, v2
	v_mov_b32_e32 v4, s91
	v_mov_b32_e32 v5, s89
	v_cndmask_b32_e32 v5, v4, v5, vcc
	v_mov_b32_e32 v4, s90
	v_mov_b32_e32 v6, s88
	v_cndmask_b32_e32 v4, v4, v6, vcc
	v_lshlrev_b32_e32 v6, 5, v2
	v_and_b32_e32 v6, 0xfe00, v6
	v_lshl_or_b32 v46, s44, 2, v6
	v_lshl_add_u64 v[4:5], v[4:5], 0, v[46:47]
	v_mov_b32_e32 v53, v47
	v_lshl_add_u64 v[4:5], v[4:5], 0, v[52:53]
	s_mov_b64 s[46:47], 0x80000
	s_mov_b32 s45, 0x80000
	v_lshl_add_u64 v[8:9], v[4:5], 0, s[46:47]
	v_add_co_u32_e32 v4, vcc, s45, v4
	v_lshrrev_b32_e32 v3, 4, v2
	s_nop 0
	v_addc_co_u32_e32 v5, vcc, 0, v5, vcc
	s_waitcnt vmcnt(0)
	v_mov_b32_e32 v4, v172
	v_mov_b32_e32 v5, v173
	v_mov_b32_e32 v6, v174
	v_mov_b32_e32 v7, v175
	v_mov_b32_e32 v8, v176
	v_mov_b32_e32 v9, v177
	v_mov_b32_e32 v10, v178
	v_mov_b32_e32 v11, v179
	s_movk_i32 s45, 0x120
	v_cvt_pk_bf16_f32 v4, v4, v5
	v_cvt_pk_bf16_f32 v5, v6, v7
	v_cvt_pk_bf16_f32 v6, v8, v9
	v_mad_u64_u32 v[8:9], s[46:47], v3, s45, v[50:51]
	s_movk_i32 s45, 0xdff
	v_cvt_pk_bf16_f32 v7, v10, v11
	ds_write_b128 v8, v[4:7]

.LBB0_2883:
	v_mov_b32_e32 v2, v51
	s_movk_i32 s52, 0x800
	v_cmp_gt_u32_e32 vcc, s52, v2
	v_mov_b32_e32 v4, s91
	v_mov_b32_e32 v5, s89
	v_cndmask_b32_e32 v5, v4, v5, vcc
	v_mov_b32_e32 v4, s90
	v_mov_b32_e32 v6, s88
	v_cndmask_b32_e32 v4, v4, v6, vcc
	v_lshlrev_b32_e32 v6, 5, v2
	v_and_b32_e32 v6, 0xfe00, v6
	v_lshl_or_b32 v46, s2, 2, v6
	v_lshl_add_u64 v[4:5], v[4:5], 0, v[46:47]
	v_mov_b32_e32 v53, v47
	v_lshl_add_u64 v[4:5], v[4:5], 0, v[52:53]
	s_mov_b64 s[54:55], 0x100000
	s_mov_b32 s52, 0x100000
	v_lshl_add_u64 v[8:9], v[4:5], 0, s[54:55]
	v_add_co_u32_e32 v4, vcc, s52, v4
	v_lshrrev_b32_e32 v3, 4, v2
	s_nop 0
	v_addc_co_u32_e32 v5, vcc, 0, v5, vcc
	global_load_dwordx4 v[80:83], v[4:5], off
	s_nop 0
	global_load_dwordx4 v[84:87], v[8:9], off offset:16
	v_add_u32_e32 v2, 0x200, v51
	s_movk_i32 s52, 0x800
	v_cmp_gt_u32_e32 vcc, s52, v2
	v_mov_b32_e32 v4, s91
	v_mov_b32_e32 v5, s89
	v_cndmask_b32_e32 v5, v4, v5, vcc
	v_mov_b32_e32 v4, s90
	v_mov_b32_e32 v6, s88
	v_cndmask_b32_e32 v4, v4, v6, vcc
	v_lshlrev_b32_e32 v6, 5, v2
	v_and_b32_e32 v6, 0xfe00, v6
	v_lshl_or_b32 v46, s2, 2, v6
	v_lshl_add_u64 v[4:5], v[4:5], 0, v[46:47]
	v_mov_b32_e32 v53, v47
	v_lshl_add_u64 v[4:5], v[4:5], 0, v[52:53]
	s_mov_b64 s[54:55], 0x100000
	s_mov_b32 s52, 0x100000
	v_lshl_add_u64 v[8:9], v[4:5], 0, s[54:55]
	v_add_co_u32_e32 v4, vcc, s52, v4
	v_lshrrev_b32_e32 v3, 4, v2
	s_nop 0
	v_addc_co_u32_e32 v5, vcc, 0, v5, vcc
	global_load_dwordx4 v[88:91], v[4:5], off
	s_nop 0
	global_load_dwordx4 v[92:95], v[8:9], off offset:16
	v_add_u32_e32 v2, 0x400, v51
	s_movk_i32 s52, 0x800
	v_cmp_gt_u32_e32 vcc, s52, v2
	v_mov_b32_e32 v4, s91
	v_mov_b32_e32 v5, s89
	v_cndmask_b32_e32 v5, v4, v5, vcc
	v_mov_b32_e32 v4, s90
	v_mov_b32_e32 v6, s88
	v_cndmask_b32_e32 v4, v4, v6, vcc
	v_lshlrev_b32_e32 v6, 5, v2
	v_and_b32_e32 v6, 0xfe00, v6
	v_lshl_or_b32 v46, s2, 2, v6
	v_lshl_add_u64 v[4:5], v[4:5], 0, v[46:47]
	v_mov_b32_e32 v53, v47
	v_lshl_add_u64 v[4:5], v[4:5], 0, v[52:53]
	s_mov_b64 s[54:55], 0x100000
	s_mov_b32 s52, 0x100000
	v_lshl_add_u64 v[8:9], v[4:5], 0, s[54:55]
	v_add_co_u32_e32 v4, vcc, s52, v4
	v_lshrrev_b32_e32 v3, 4, v2
	s_nop 0
	v_addc_co_u32_e32 v5, vcc, 0, v5, vcc
	global_load_dwordx4 v[96:99], v[4:5], off
	s_nop 0
	global_load_dwordx4 v[100:103], v[8:9], off offset:16
	v_add_u32_e32 v2, 0x600, v51
	s_movk_i32 s52, 0x800
	v_cmp_gt_u32_e32 vcc, s52, v2
	v_mov_b32_e32 v4, s91
	v_mov_b32_e32 v5, s89
	v_cndmask_b32_e32 v5, v4, v5, vcc
	v_mov_b32_e32 v4, s90
	v_mov_b32_e32 v6, s88
	v_cndmask_b32_e32 v4, v4, v6, vcc
	v_lshlrev_b32_e32 v6, 5, v2
	v_and_b32_e32 v6, 0xfe00, v6
	v_lshl_or_b32 v46, s2, 2, v6
	v_lshl_add_u64 v[4:5], v[4:5], 0, v[46:47]
	v_mov_b32_e32 v53, v47
	v_lshl_add_u64 v[4:5], v[4:5], 0, v[52:53]
	s_mov_b64 s[54:55], 0x100000
	s_mov_b32 s52, 0x100000
	v_lshl_add_u64 v[8:9], v[4:5], 0, s[54:55]
	v_add_co_u32_e32 v4, vcc, s52, v4
	v_lshrrev_b32_e32 v3, 4, v2
	s_nop 0
	v_addc_co_u32_e32 v5, vcc, 0, v5, vcc
	global_load_dwordx4 v[104:107], v[4:5], off
	s_nop 0
	global_load_dwordx4 v[108:111], v[8:9], off offset:16
	v_add_u32_e32 v2, 0x800, v51
	s_movk_i32 s52, 0x800
	v_cmp_gt_u32_e32 vcc, s52, v2
	v_mov_b32_e32 v4, s91
	v_mov_b32_e32 v5, s89
	v_cndmask_b32_e32 v5, v4, v5, vcc
	v_mov_b32_e32 v4, s90
	v_mov_b32_e32 v6, s88
	v_cndmask_b32_e32 v4, v4, v6, vcc
	v_lshlrev_b32_e32 v6, 5, v2
	v_and_b32_e32 v6, 0xfe00, v6
	v_lshl_or_b32 v46, s2, 2, v6
	v_lshl_add_u64 v[4:5], v[4:5], 0, v[46:47]
	v_mov_b32_e32 v53, v47
	v_lshl_add_u64 v[4:5], v[4:5], 0, v[52:53]
	s_mov_b64 s[54:55], 0x100000
	s_mov_b32 s52, 0x100000
	v_lshl_add_u64 v[8:9], v[4:5], 0, s[54:55]
	v_add_co_u32_e32 v4, vcc, s52, v4
	v_lshrrev_b32_e32 v3, 4, v2
	s_nop 0
	v_addc_co_u32_e32 v5, vcc, 0, v5, vcc
	global_load_dwordx4 v[148:151], v[4:5], off
	s_nop 0
	global_load_dwordx4 v[152:155], v[8:9], off offset:16
	v_add_u32_e32 v2, 0xa00, v51
	s_movk_i32 s52, 0x800
	v_cmp_gt_u32_e32 vcc, s52, v2
	v_mov_b32_e32 v4, s91
	v_mov_b32_e32 v5, s89
	v_cndmask_b32_e32 v5, v4, v5, vcc
	v_mov_b32_e32 v4, s90
	v_mov_b32_e32 v6, s88
	v_cndmask_b32_e32 v4, v4, v6, vcc
	v_lshlrev_b32_e32 v6, 5, v2
	v_and_b32_e32 v6, 0xfe00, v6
	v_lshl_or_b32 v46, s2, 2, v6
	v_lshl_add_u64 v[4:5], v[4:5], 0, v[46:47]
	v_mov_b32_e32 v53, v47
	v_lshl_add_u64 v[4:5], v[4:5], 0, v[52:53]
	s_mov_b64 s[54:55], 0x100000
	s_mov_b32 s52, 0x100000
	v_lshl_add_u64 v[8:9], v[4:5], 0, s[54:55]
	v_add_co_u32_e32 v4, vcc, s52, v4
	v_lshrrev_b32_e32 v3, 4, v2
	s_nop 0
	v_addc_co_u32_e32 v5, vcc, 0, v5, vcc
	global_load_dwordx4 v[156:159], v[4:5], off
	s_nop 0
	global_load_dwordx4 v[160:163], v[8:9], off offset:16
	v_add_u32_e32 v2, 0xc00, v51
	s_movk_i32 s52, 0x800
	v_cmp_gt_u32_e32 vcc, s52, v2
	v_mov_b32_e32 v4, s91
	v_mov_b32_e32 v5, s89
	v_cndmask_b32_e32 v5, v4, v5, vcc
	v_mov_b32_e32 v4, s90
	v_mov_b32_e32 v6, s88
	v_cndmask_b32_e32 v4, v4, v6, vcc
	v_lshlrev_b32_e32 v6, 5, v2
	v_and_b32_e32 v6, 0xfe00, v6
	v_lshl_or_b32 v46, s2, 2, v6
	v_lshl_add_u64 v[4:5], v[4:5], 0, v[46:47]
	v_mov_b32_e32 v53, v47
	v_lshl_add_u64 v[4:5], v[4:5], 0, v[52:53]
	s_mov_b64 s[54:55], 0x100000
	s_mov_b32 s52, 0x100000
	v_lshl_add_u64 v[8:9], v[4:5], 0, s[54:55]
	v_add_co_u32_e32 v4, vcc, s52, v4
	v_lshrrev_b32_e32 v3, 4, v2
	s_nop 0
	v_addc_co_u32_e32 v5, vcc, 0, v5, vcc
	global_load_dwordx4 v[164:167], v[4:5], off
	s_nop 0
	global_load_dwordx4 v[168:171], v[8:9], off offset:16
	v_add_u32_e32 v2, 0xe00, v51
	s_movk_i32 s52, 0x800
	v_cmp_gt_u32_e32 vcc, s52, v2
	v_mov_b32_e32 v4, s91
	v_mov_b32_e32 v5, s89
	v_cndmask_b32_e32 v5, v4, v5, vcc
	v_mov_b32_e32 v4, s90
	v_mov_b32_e32 v6, s88
	v_cndmask_b32_e32 v4, v4, v6, vcc
	v_lshlrev_b32_e32 v6, 5, v2
	v_and_b32_e32 v6, 0xfe00, v6
	v_lshl_or_b32 v46, s2, 2, v6
	v_lshl_add_u64 v[4:5], v[4:5], 0, v[46:47]
	v_mov_b32_e32 v53, v47
	v_lshl_add_u64 v[4:5], v[4:5], 0, v[52:53]
	s_mov_b64 s[54:55], 0x100000
	s_mov_b32 s52, 0x100000
	v_lshl_add_u64 v[8:9], v[4:5], 0, s[54:55]
	v_add_co_u32_e32 v4, vcc, s52, v4
	v_lshrrev_b32_e32 v3, 4, v2
	s_nop 0
	v_addc_co_u32_e32 v5, vcc, 0, v5, vcc
	global_load_dwordx4 v[172:175], v[4:5], off
	s_nop 0
	global_load_dwordx4 v[176:179], v[8:9], off offset:16
	v_mov_b32_e32 v2, v51
	s_movk_i32 s52, 0x800
	v_cmp_gt_u32_e32 vcc, s52, v2
	v_mov_b32_e32 v4, s91
	v_mov_b32_e32 v5, s89
	v_cndmask_b32_e32 v5, v4, v5, vcc
	v_mov_b32_e32 v4, s90
	v_mov_b32_e32 v6, s88
	v_cndmask_b32_e32 v4, v4, v6, vcc
	v_lshlrev_b32_e32 v6, 5, v2
	v_and_b32_e32 v6, 0xfe00, v6
	v_lshl_or_b32 v46, s2, 2, v6
	v_lshl_add_u64 v[4:5], v[4:5], 0, v[46:47]
	v_mov_b32_e32 v53, v47
	v_lshl_add_u64 v[4:5], v[4:5], 0, v[52:53]
	s_mov_b64 s[54:55], 0x100000
	s_mov_b32 s52, 0x100000
	v_lshl_add_u64 v[8:9], v[4:5], 0, s[54:55]
	v_add_co_u32_e32 v4, vcc, s52, v4
	v_lshrrev_b32_e32 v3, 4, v2
	s_nop 0
	v_addc_co_u32_e32 v5, vcc, 0, v5, vcc
	s_waitcnt vmcnt(14)
	v_mov_b32_e32 v4, v80
	v_mov_b32_e32 v5, v81
	v_mov_b32_e32 v6, v82
	v_mov_b32_e32 v7, v83
	v_mov_b32_e32 v8, v84
	v_mov_b32_e32 v9, v85
	v_mov_b32_e32 v10, v86
	v_mov_b32_e32 v11, v87
	s_movk_i32 s52, 0x120
	v_cvt_pk_bf16_f32 v4, v4, v5
	v_cvt_pk_bf16_f32 v5, v6, v7
	v_cvt_pk_bf16_f32 v6, v8, v9
	v_mad_u64_u32 v[8:9], s[54:55], v3, s52, v[50:51]
	s_movk_i32 s52, 0xdff
	v_cvt_pk_bf16_f32 v7, v10, v11
	ds_write_b128 v8, v[4:7]
	v_add_u32_e32 v2, 0x200, v51
	s_movk_i32 s52, 0x800
	v_cmp_gt_u32_e32 vcc, s52, v2
	v_mov_b32_e32 v4, s91
	v_mov_b32_e32 v5, s89
	v_cndmask_b32_e32 v5, v4, v5, vcc
	v_mov_b32_e32 v4, s90
	v_mov_b32_e32 v6, s88
	v_cndmask_b32_e32 v4, v4, v6, vcc
	v_lshlrev_b32_e32 v6, 5, v2
	v_and_b32_e32 v6, 0xfe00, v6
	v_lshl_or_b32 v46, s2, 2, v6
	v_lshl_add_u64 v[4:5], v[4:5], 0, v[46:47]
	v_mov_b32_e32 v53, v47
	v_lshl_add_u64 v[4:5], v[4:5], 0, v[52:53]
	s_mov_b64 s[54:55], 0x100000
	s_mov_b32 s52, 0x100000
	v_lshl_add_u64 v[8:9], v[4:5], 0, s[54:55]
	v_add_co_u32_e32 v4, vcc, s52, v4
	v_lshrrev_b32_e32 v3, 4, v2
	s_nop 0
	v_addc_co_u32_e32 v5, vcc, 0, v5, vcc
	s_waitcnt vmcnt(12)
	v_mov_b32_e32 v4, v88
	v_mov_b32_e32 v5, v89
	v_mov_b32_e32 v6, v90
	v_mov_b32_e32 v7, v91
	v_mov_b32_e32 v8, v92
	v_mov_b32_e32 v9, v93
	v_mov_b32_e32 v10, v94
	v_mov_b32_e32 v11, v95
	s_movk_i32 s52, 0x120
	v_cvt_pk_bf16_f32 v4, v4, v5
	v_cvt_pk_bf16_f32 v5, v6, v7
	v_cvt_pk_bf16_f32 v6, v8, v9
	v_mad_u64_u32 v[8:9], s[54:55], v3, s52, v[50:51]
	s_movk_i32 s52, 0xdff
	v_cvt_pk_bf16_f32 v7, v10, v11
	ds_write_b128 v8, v[4:7]
	v_add_u32_e32 v2, 0x400, v51
	s_movk_i32 s52, 0x800
	v_cmp_gt_u32_e32 vcc, s52, v2
	v_mov_b32_e32 v4, s91
	v_mov_b32_e32 v5, s89
	v_cndmask_b32_e32 v5, v4, v5, vcc
	v_mov_b32_e32 v4, s90
	v_mov_b32_e32 v6, s88
	v_cndmask_b32_e32 v4, v4, v6, vcc
	v_lshlrev_b32_e32 v6, 5, v2
	v_and_b32_e32 v6, 0xfe00, v6
	v_lshl_or_b32 v46, s2, 2, v6
	v_lshl_add_u64 v[4:5], v[4:5], 0, v[46:47]
	v_mov_b32_e32 v53, v47
	v_lshl_add_u64 v[4:5], v[4:5], 0, v[52:53]
	s_mov_b64 s[54:55], 0x100000
	s_mov_b32 s52, 0x100000
	v_lshl_add_u64 v[8:9], v[4:5], 0, s[54:55]
	v_add_co_u32_e32 v4, vcc, s52, v4
	v_lshrrev_b32_e32 v3, 4, v2
	s_nop 0
	v_addc_co_u32_e32 v5, vcc, 0, v5, vcc
	s_waitcnt vmcnt(10)
	v_mov_b32_e32 v4, v96
	v_mov_b32_e32 v5, v97
	v_mov_b32_e32 v6, v98
	v_mov_b32_e32 v7, v99
	v_mov_b32_e32 v8, v100
	v_mov_b32_e32 v9, v101
	v_mov_b32_e32 v10, v102
	v_mov_b32_e32 v11, v103
	s_movk_i32 s52, 0x120
	v_cvt_pk_bf16_f32 v4, v4, v5
	v_cvt_pk_bf16_f32 v5, v6, v7
	v_cvt_pk_bf16_f32 v6, v8, v9
	v_mad_u64_u32 v[8:9], s[54:55], v3, s52, v[50:51]
	s_movk_i32 s52, 0xdff
	v_cvt_pk_bf16_f32 v7, v10, v11
	ds_write_b128 v8, v[4:7]
	v_add_u32_e32 v2, 0x600, v51
	s_movk_i32 s52, 0x800
	v_cmp_gt_u32_e32 vcc, s52, v2
	v_mov_b32_e32 v4, s91
	v_mov_b32_e32 v5, s89
	v_cndmask_b32_e32 v5, v4, v5, vcc
	v_mov_b32_e32 v4, s90
	v_mov_b32_e32 v6, s88
	v_cndmask_b32_e32 v4, v4, v6, vcc
	v_lshlrev_b32_e32 v6, 5, v2
	v_and_b32_e32 v6, 0xfe00, v6
	v_lshl_or_b32 v46, s2, 2, v6
	v_lshl_add_u64 v[4:5], v[4:5], 0, v[46:47]
	v_mov_b32_e32 v53, v47
	v_lshl_add_u64 v[4:5], v[4:5], 0, v[52:53]
	s_mov_b64 s[54:55], 0x100000
	s_mov_b32 s52, 0x100000
	v_lshl_add_u64 v[8:9], v[4:5], 0, s[54:55]
	v_add_co_u32_e32 v4, vcc, s52, v4
	v_lshrrev_b32_e32 v3, 4, v2
	s_nop 0
	v_addc_co_u32_e32 v5, vcc, 0, v5, vcc
	s_waitcnt vmcnt(8)
	v_mov_b32_e32 v4, v104
	v_mov_b32_e32 v5, v105
	v_mov_b32_e32 v6, v106
	v_mov_b32_e32 v7, v107
	v_mov_b32_e32 v8, v108
	v_mov_b32_e32 v9, v109
	v_mov_b32_e32 v10, v110
	v_mov_b32_e32 v11, v111
	s_movk_i32 s52, 0x120
	v_cvt_pk_bf16_f32 v4, v4, v5
	v_cvt_pk_bf16_f32 v5, v6, v7
	v_cvt_pk_bf16_f32 v6, v8, v9
	v_mad_u64_u32 v[8:9], s[54:55], v3, s52, v[50:51]
	s_movk_i32 s52, 0xdff
	v_cvt_pk_bf16_f32 v7, v10, v11
	ds_write_b128 v8, v[4:7]
	v_add_u32_e32 v2, 0x800, v51
	s_movk_i32 s52, 0x800
	v_cmp_gt_u32_e32 vcc, s52, v2
	v_mov_b32_e32 v4, s91
	v_mov_b32_e32 v5, s89
	v_cndmask_b32_e32 v5, v4, v5, vcc
	v_mov_b32_e32 v4, s90
	v_mov_b32_e32 v6, s88
	v_cndmask_b32_e32 v4, v4, v6, vcc
	v_lshlrev_b32_e32 v6, 5, v2
	v_and_b32_e32 v6, 0xfe00, v6
	v_lshl_or_b32 v46, s2, 2, v6
	v_lshl_add_u64 v[4:5], v[4:5], 0, v[46:47]
	v_mov_b32_e32 v53, v47
	v_lshl_add_u64 v[4:5], v[4:5], 0, v[52:53]
	s_mov_b64 s[54:55], 0x100000
	s_mov_b32 s52, 0x100000
	v_lshl_add_u64 v[8:9], v[4:5], 0, s[54:55]
	v_add_co_u32_e32 v4, vcc, s52, v4
	v_lshrrev_b32_e32 v3, 4, v2
	s_nop 0
	v_addc_co_u32_e32 v5, vcc, 0, v5, vcc
	s_waitcnt vmcnt(6)
	v_mov_b32_e32 v4, v148
	v_mov_b32_e32 v5, v149
	v_mov_b32_e32 v6, v150
	v_mov_b32_e32 v7, v151
	v_mov_b32_e32 v8, v152
	v_mov_b32_e32 v9, v153
	v_mov_b32_e32 v10, v154
	v_mov_b32_e32 v11, v155
	s_movk_i32 s52, 0x120
	v_cvt_pk_bf16_f32 v4, v4, v5
	v_cvt_pk_bf16_f32 v5, v6, v7
	v_cvt_pk_bf16_f32 v6, v8, v9
	v_mad_u64_u32 v[8:9], s[54:55], v3, s52, v[50:51]
	s_movk_i32 s52, 0xdff
	v_cvt_pk_bf16_f32 v7, v10, v11
	ds_write_b128 v8, v[4:7]
	v_add_u32_e32 v2, 0xa00, v51
	s_movk_i32 s52, 0x800
	v_cmp_gt_u32_e32 vcc, s52, v2
	v_mov_b32_e32 v4, s91
	v_mov_b32_e32 v5, s89
	v_cndmask_b32_e32 v5, v4, v5, vcc
	v_mov_b32_e32 v4, s90
	v_mov_b32_e32 v6, s88
	v_cndmask_b32_e32 v4, v4, v6, vcc
	v_lshlrev_b32_e32 v6, 5, v2
	v_and_b32_e32 v6, 0xfe00, v6
	v_lshl_or_b32 v46, s2, 2, v6
	v_lshl_add_u64 v[4:5], v[4:5], 0, v[46:47]
	v_mov_b32_e32 v53, v47
	v_lshl_add_u64 v[4:5], v[4:5], 0, v[52:53]
	s_mov_b64 s[54:55], 0x100000
	s_mov_b32 s52, 0x100000
	v_lshl_add_u64 v[8:9], v[4:5], 0, s[54:55]
	v_add_co_u32_e32 v4, vcc, s52, v4
	v_lshrrev_b32_e32 v3, 4, v2
	s_nop 0
	v_addc_co_u32_e32 v5, vcc, 0, v5, vcc
	s_waitcnt vmcnt(4)
	v_mov_b32_e32 v4, v156
	v_mov_b32_e32 v5, v157
	v_mov_b32_e32 v6, v158
	v_mov_b32_e32 v7, v159
	v_mov_b32_e32 v8, v160
	v_mov_b32_e32 v9, v161
	v_mov_b32_e32 v10, v162
	v_mov_b32_e32 v11, v163
	s_movk_i32 s52, 0x120
	v_cvt_pk_bf16_f32 v4, v4, v5
	v_cvt_pk_bf16_f32 v5, v6, v7
	v_cvt_pk_bf16_f32 v6, v8, v9
	v_mad_u64_u32 v[8:9], s[54:55], v3, s52, v[50:51]
	s_movk_i32 s52, 0xdff
	v_cvt_pk_bf16_f32 v7, v10, v11
	ds_write_b128 v8, v[4:7]
	v_add_u32_e32 v2, 0xc00, v51
	s_movk_i32 s52, 0x800
	v_cmp_gt_u32_e32 vcc, s52, v2
	v_mov_b32_e32 v4, s91
	v_mov_b32_e32 v5, s89
	v_cndmask_b32_e32 v5, v4, v5, vcc
	v_mov_b32_e32 v4, s90
	v_mov_b32_e32 v6, s88
	v_cndmask_b32_e32 v4, v4, v6, vcc
	v_lshlrev_b32_e32 v6, 5, v2
	v_and_b32_e32 v6, 0xfe00, v6
	v_lshl_or_b32 v46, s2, 2, v6
	v_lshl_add_u64 v[4:5], v[4:5], 0, v[46:47]
	v_mov_b32_e32 v53, v47
	v_lshl_add_u64 v[4:5], v[4:5], 0, v[52:53]
	s_mov_b64 s[54:55], 0x100000
	s_mov_b32 s52, 0x100000
	v_lshl_add_u64 v[8:9], v[4:5], 0, s[54:55]
	v_add_co_u32_e32 v4, vcc, s52, v4
	v_lshrrev_b32_e32 v3, 4, v2
	s_nop 0
	v_addc_co_u32_e32 v5, vcc, 0, v5, vcc
	s_waitcnt vmcnt(2)
	v_mov_b32_e32 v4, v164
	v_mov_b32_e32 v5, v165
	v_mov_b32_e32 v6, v166
	v_mov_b32_e32 v7, v167
	v_mov_b32_e32 v8, v168
	v_mov_b32_e32 v9, v169
	v_mov_b32_e32 v10, v170
	v_mov_b32_e32 v11, v171
	s_movk_i32 s52, 0x120
	v_cvt_pk_bf16_f32 v4, v4, v5
	v_cvt_pk_bf16_f32 v5, v6, v7
	v_cvt_pk_bf16_f32 v6, v8, v9
	v_mad_u64_u32 v[8:9], s[54:55], v3, s52, v[50:51]
	s_movk_i32 s52, 0xdff
	v_cvt_pk_bf16_f32 v7, v10, v11
	ds_write_b128 v8, v[4:7]
	v_add_u32_e32 v2, 0xe00, v51
	s_movk_i32 s52, 0x800
	v_cmp_gt_u32_e32 vcc, s52, v2
	v_mov_b32_e32 v4, s91
	v_mov_b32_e32 v5, s89
	v_cndmask_b32_e32 v5, v4, v5, vcc
	v_mov_b32_e32 v4, s90
	v_mov_b32_e32 v6, s88
	v_cndmask_b32_e32 v4, v4, v6, vcc
	v_lshlrev_b32_e32 v6, 5, v2
	v_and_b32_e32 v6, 0xfe00, v6
	v_lshl_or_b32 v46, s2, 2, v6
	v_lshl_add_u64 v[4:5], v[4:5], 0, v[46:47]
	v_mov_b32_e32 v53, v47
	v_lshl_add_u64 v[4:5], v[4:5], 0, v[52:53]
	s_mov_b64 s[54:55], 0x100000
	s_mov_b32 s52, 0x100000
	v_lshl_add_u64 v[8:9], v[4:5], 0, s[54:55]
	v_add_co_u32_e32 v4, vcc, s52, v4
	v_lshrrev_b32_e32 v3, 4, v2
	s_nop 0
	v_addc_co_u32_e32 v5, vcc, 0, v5, vcc
	s_waitcnt vmcnt(0)
	v_mov_b32_e32 v4, v172
	v_mov_b32_e32 v5, v173
	v_mov_b32_e32 v6, v174
	v_mov_b32_e32 v7, v175
	v_mov_b32_e32 v8, v176
	v_mov_b32_e32 v9, v177
	v_mov_b32_e32 v10, v178
	v_mov_b32_e32 v11, v179
	s_movk_i32 s52, 0x120
	v_cvt_pk_bf16_f32 v4, v4, v5
	v_cvt_pk_bf16_f32 v5, v6, v7
	v_cvt_pk_bf16_f32 v6, v8, v9
	v_mad_u64_u32 v[8:9], s[54:55], v3, s52, v[50:51]
	s_movk_i32 s52, 0xdff
	v_cvt_pk_bf16_f32 v7, v10, v11
	ds_write_b128 v8, v[4:7]

.LBB0_3867:
	v_mov_b32_e32 v2, v119
	v_mov_b32_e32 v3, s91
	v_mov_b32_e32 v4, s89
	v_lshlrev_b32_e32 v8, 5, v2
	v_cmp_gt_u32_e32 vcc, s81, v2
	v_mov_b32_e32 v6, s90
	v_mov_b32_e32 v7, s88
	v_cndmask_b32_e32 v5, v3, v4, vcc
	v_and_b32_e32 v3, 0xfe00, v8
	v_cndmask_b32_e32 v4, v6, v7, vcc
	v_lshl_or_b32 v114, s42, 2, v3
	v_mov_b32_e32 v121, v115
	v_lshl_add_u64 v[4:5], v[4:5], 0, v[114:115]
	v_lshl_add_u64 v[4:5], v[4:5], 0, v[120:121]
	v_lshl_add_u64 v[8:9], v[4:5], 0, s[66:67]
	v_add_co_u32_e32 v4, vcc, s82, v4
	v_lshrrev_b32_e32 v3, 4, v2
	s_nop 0
	v_addc_co_u32_e32 v5, vcc, 0, v5, vcc
	global_load_dwordx4 v[80:83], v[4:5], off
	s_nop 0
	global_load_dwordx4 v[84:87], v[8:9], off offset:16
	v_add_u32_e32 v2, 0x200, v119
	v_mov_b32_e32 v3, s91
	v_mov_b32_e32 v4, s89
	v_lshlrev_b32_e32 v8, 5, v2
	v_cmp_gt_u32_e32 vcc, s81, v2
	v_mov_b32_e32 v6, s90
	v_mov_b32_e32 v7, s88
	v_cndmask_b32_e32 v5, v3, v4, vcc
	v_and_b32_e32 v3, 0xfe00, v8
	v_cndmask_b32_e32 v4, v6, v7, vcc
	v_lshl_or_b32 v114, s42, 2, v3
	v_mov_b32_e32 v121, v115
	v_lshl_add_u64 v[4:5], v[4:5], 0, v[114:115]
	v_lshl_add_u64 v[4:5], v[4:5], 0, v[120:121]
	v_lshl_add_u64 v[8:9], v[4:5], 0, s[66:67]
	v_add_co_u32_e32 v4, vcc, s82, v4
	v_lshrrev_b32_e32 v3, 4, v2
	s_nop 0
	v_addc_co_u32_e32 v5, vcc, 0, v5, vcc
	global_load_dwordx4 v[88:91], v[4:5], off
	s_nop 0
	global_load_dwordx4 v[92:95], v[8:9], off offset:16
	v_add_u32_e32 v2, 0x400, v119
	v_mov_b32_e32 v3, s91
	v_mov_b32_e32 v4, s89
	v_lshlrev_b32_e32 v8, 5, v2
	v_cmp_gt_u32_e32 vcc, s81, v2
	v_mov_b32_e32 v6, s90
	v_mov_b32_e32 v7, s88
	v_cndmask_b32_e32 v5, v3, v4, vcc
	v_and_b32_e32 v3, 0xfe00, v8
	v_cndmask_b32_e32 v4, v6, v7, vcc
	v_lshl_or_b32 v114, s42, 2, v3
	v_mov_b32_e32 v121, v115
	v_lshl_add_u64 v[4:5], v[4:5], 0, v[114:115]
	v_lshl_add_u64 v[4:5], v[4:5], 0, v[120:121]
	v_lshl_add_u64 v[8:9], v[4:5], 0, s[66:67]
	v_add_co_u32_e32 v4, vcc, s82, v4
	v_lshrrev_b32_e32 v3, 4, v2
	s_nop 0
	v_addc_co_u32_e32 v5, vcc, 0, v5, vcc
	global_load_dwordx4 v[96:99], v[4:5], off
	s_nop 0
	global_load_dwordx4 v[100:103], v[8:9], off offset:16
	v_add_u32_e32 v2, 0x600, v119
	v_mov_b32_e32 v3, s91
	v_mov_b32_e32 v4, s89
	v_lshlrev_b32_e32 v8, 5, v2
	v_cmp_gt_u32_e32 vcc, s81, v2
	v_mov_b32_e32 v6, s90
	v_mov_b32_e32 v7, s88
	v_cndmask_b32_e32 v5, v3, v4, vcc
	v_and_b32_e32 v3, 0xfe00, v8
	v_cndmask_b32_e32 v4, v6, v7, vcc
	v_lshl_or_b32 v114, s42, 2, v3
	v_mov_b32_e32 v121, v115
	v_lshl_add_u64 v[4:5], v[4:5], 0, v[114:115]
	v_lshl_add_u64 v[4:5], v[4:5], 0, v[120:121]
	v_lshl_add_u64 v[8:9], v[4:5], 0, s[66:67]
	v_add_co_u32_e32 v4, vcc, s82, v4
	v_lshrrev_b32_e32 v3, 4, v2
	s_nop 0
	v_addc_co_u32_e32 v5, vcc, 0, v5, vcc
	global_load_dwordx4 v[104:107], v[4:5], off
	s_nop 0
	global_load_dwordx4 v[108:111], v[8:9], off offset:16
	v_add_u32_e32 v2, 0x800, v119
	v_mov_b32_e32 v3, s91
	v_mov_b32_e32 v4, s89
	v_lshlrev_b32_e32 v8, 5, v2
	v_cmp_gt_u32_e32 vcc, s81, v2
	v_mov_b32_e32 v6, s90
	v_mov_b32_e32 v7, s88
	v_cndmask_b32_e32 v5, v3, v4, vcc
	v_and_b32_e32 v3, 0xfe00, v8
	v_cndmask_b32_e32 v4, v6, v7, vcc
	v_lshl_or_b32 v114, s42, 2, v3
	v_mov_b32_e32 v121, v115
	v_lshl_add_u64 v[4:5], v[4:5], 0, v[114:115]
	v_lshl_add_u64 v[4:5], v[4:5], 0, v[120:121]
	v_lshl_add_u64 v[8:9], v[4:5], 0, s[66:67]
	v_add_co_u32_e32 v4, vcc, s82, v4
	v_lshrrev_b32_e32 v3, 4, v2
	s_nop 0
	v_addc_co_u32_e32 v5, vcc, 0, v5, vcc
	global_load_dwordx4 v[148:151], v[4:5], off
	s_nop 0
	global_load_dwordx4 v[152:155], v[8:9], off offset:16
	v_add_u32_e32 v2, 0xa00, v119
	v_mov_b32_e32 v3, s91
	v_mov_b32_e32 v4, s89
	v_lshlrev_b32_e32 v8, 5, v2
	v_cmp_gt_u32_e32 vcc, s81, v2
	v_mov_b32_e32 v6, s90
	v_mov_b32_e32 v7, s88
	v_cndmask_b32_e32 v5, v3, v4, vcc
	v_and_b32_e32 v3, 0xfe00, v8
	v_cndmask_b32_e32 v4, v6, v7, vcc
	v_lshl_or_b32 v114, s42, 2, v3
	v_mov_b32_e32 v121, v115
	v_lshl_add_u64 v[4:5], v[4:5], 0, v[114:115]
	v_lshl_add_u64 v[4:5], v[4:5], 0, v[120:121]
	v_lshl_add_u64 v[8:9], v[4:5], 0, s[66:67]
	v_add_co_u32_e32 v4, vcc, s82, v4
	v_lshrrev_b32_e32 v3, 4, v2
	s_nop 0
	v_addc_co_u32_e32 v5, vcc, 0, v5, vcc
	global_load_dwordx4 v[156:159], v[4:5], off
	s_nop 0
	global_load_dwordx4 v[160:163], v[8:9], off offset:16
	v_add_u32_e32 v2, 0xc00, v119
	v_mov_b32_e32 v3, s91
	v_mov_b32_e32 v4, s89
	v_lshlrev_b32_e32 v8, 5, v2
	v_cmp_gt_u32_e32 vcc, s81, v2
	v_mov_b32_e32 v6, s90
	v_mov_b32_e32 v7, s88
	v_cndmask_b32_e32 v5, v3, v4, vcc
	v_and_b32_e32 v3, 0xfe00, v8
	v_cndmask_b32_e32 v4, v6, v7, vcc
	v_lshl_or_b32 v114, s42, 2, v3
	v_mov_b32_e32 v121, v115
	v_lshl_add_u64 v[4:5], v[4:5], 0, v[114:115]
	v_lshl_add_u64 v[4:5], v[4:5], 0, v[120:121]
	v_lshl_add_u64 v[8:9], v[4:5], 0, s[66:67]
	v_add_co_u32_e32 v4, vcc, s82, v4
	v_lshrrev_b32_e32 v3, 4, v2
	s_nop 0
	v_addc_co_u32_e32 v5, vcc, 0, v5, vcc
	global_load_dwordx4 v[164:167], v[4:5], off
	s_nop 0
	global_load_dwordx4 v[168:171], v[8:9], off offset:16
	v_add_u32_e32 v2, 0xe00, v119
	v_mov_b32_e32 v3, s91
	v_mov_b32_e32 v4, s89
	v_lshlrev_b32_e32 v8, 5, v2
	v_cmp_gt_u32_e32 vcc, s81, v2
	v_mov_b32_e32 v6, s90
	v_mov_b32_e32 v7, s88
	v_cndmask_b32_e32 v5, v3, v4, vcc
	v_and_b32_e32 v3, 0xfe00, v8
	v_cndmask_b32_e32 v4, v6, v7, vcc
	v_lshl_or_b32 v114, s42, 2, v3
	v_mov_b32_e32 v121, v115
	v_lshl_add_u64 v[4:5], v[4:5], 0, v[114:115]
	v_lshl_add_u64 v[4:5], v[4:5], 0, v[120:121]
	v_lshl_add_u64 v[8:9], v[4:5], 0, s[66:67]
	v_add_co_u32_e32 v4, vcc, s82, v4
	v_lshrrev_b32_e32 v3, 4, v2
	s_nop 0
	v_addc_co_u32_e32 v5, vcc, 0, v5, vcc
	global_load_dwordx4 v[172:175], v[4:5], off
	s_nop 0
	global_load_dwordx4 v[176:179], v[8:9], off offset:16
	v_mov_b32_e32 v2, v119
	v_mov_b32_e32 v3, s91
	v_mov_b32_e32 v4, s89
	v_lshlrev_b32_e32 v8, 5, v2
	v_cmp_gt_u32_e32 vcc, s81, v2
	v_mov_b32_e32 v6, s90
	v_mov_b32_e32 v7, s88
	v_cndmask_b32_e32 v5, v3, v4, vcc
	v_and_b32_e32 v3, 0xfe00, v8
	v_cndmask_b32_e32 v4, v6, v7, vcc
	v_lshl_or_b32 v114, s42, 2, v3
	v_mov_b32_e32 v121, v115
	v_lshl_add_u64 v[4:5], v[4:5], 0, v[114:115]
	v_lshl_add_u64 v[4:5], v[4:5], 0, v[120:121]
	v_lshl_add_u64 v[8:9], v[4:5], 0, s[66:67]
	v_add_co_u32_e32 v4, vcc, s82, v4
	v_lshrrev_b32_e32 v3, 4, v2
	s_nop 0
	v_addc_co_u32_e32 v5, vcc, 0, v5, vcc
	s_waitcnt vmcnt(14)
	v_mov_b32_e32 v4, v80
	v_mov_b32_e32 v5, v81
	v_mov_b32_e32 v6, v82
	v_mov_b32_e32 v7, v83
	v_mov_b32_e32 v8, v84
	v_mov_b32_e32 v9, v85
	v_mov_b32_e32 v10, v86
	v_mov_b32_e32 v11, v87
	v_mad_u64_u32 v[12:13], s[46:47], v3, s3, v[118:119]
	v_cvt_pk_bf16_f32 v4, v4, v5
	v_cvt_pk_bf16_f32 v5, v6, v7
	v_cvt_pk_bf16_f32 v6, v8, v9
	v_cvt_pk_bf16_f32 v7, v10, v11
	ds_write_b128 v12, v[4:7]
	v_add_u32_e32 v2, 0x200, v119
	v_mov_b32_e32 v3, s91
	v_mov_b32_e32 v4, s89
	v_lshlrev_b32_e32 v8, 5, v2
	v_cmp_gt_u32_e32 vcc, s81, v2
	v_mov_b32_e32 v6, s90
	v_mov_b32_e32 v7, s88
	v_cndmask_b32_e32 v5, v3, v4, vcc
	v_and_b32_e32 v3, 0xfe00, v8
	v_cndmask_b32_e32 v4, v6, v7, vcc
	v_lshl_or_b32 v114, s42, 2, v3
	v_mov_b32_e32 v121, v115
	v_lshl_add_u64 v[4:5], v[4:5], 0, v[114:115]
	v_lshl_add_u64 v[4:5], v[4:5], 0, v[120:121]
	v_lshl_add_u64 v[8:9], v[4:5], 0, s[66:67]
	v_add_co_u32_e32 v4, vcc, s82, v4
	v_lshrrev_b32_e32 v3, 4, v2
	s_nop 0
	v_addc_co_u32_e32 v5, vcc, 0, v5, vcc
	s_waitcnt vmcnt(12)
	v_mov_b32_e32 v4, v88
	v_mov_b32_e32 v5, v89
	v_mov_b32_e32 v6, v90
	v_mov_b32_e32 v7, v91
	v_mov_b32_e32 v8, v92
	v_mov_b32_e32 v9, v93
	v_mov_b32_e32 v10, v94
	v_mov_b32_e32 v11, v95
	v_mad_u64_u32 v[12:13], s[46:47], v3, s3, v[118:119]
	v_cvt_pk_bf16_f32 v4, v4, v5
	v_cvt_pk_bf16_f32 v5, v6, v7
	v_cvt_pk_bf16_f32 v6, v8, v9
	v_cvt_pk_bf16_f32 v7, v10, v11
	ds_write_b128 v12, v[4:7]
	v_add_u32_e32 v2, 0x400, v119
	v_mov_b32_e32 v3, s91
	v_mov_b32_e32 v4, s89
	v_lshlrev_b32_e32 v8, 5, v2
	v_cmp_gt_u32_e32 vcc, s81, v2
	v_mov_b32_e32 v6, s90
	v_mov_b32_e32 v7, s88
	v_cndmask_b32_e32 v5, v3, v4, vcc
	v_and_b32_e32 v3, 0xfe00, v8
	v_cndmask_b32_e32 v4, v6, v7, vcc
	v_lshl_or_b32 v114, s42, 2, v3
	v_mov_b32_e32 v121, v115
	v_lshl_add_u64 v[4:5], v[4:5], 0, v[114:115]
	v_lshl_add_u64 v[4:5], v[4:5], 0, v[120:121]
	v_lshl_add_u64 v[8:9], v[4:5], 0, s[66:67]
	v_add_co_u32_e32 v4, vcc, s82, v4
	v_lshrrev_b32_e32 v3, 4, v2
	s_nop 0
	v_addc_co_u32_e32 v5, vcc, 0, v5, vcc
	s_waitcnt vmcnt(10)
	v_mov_b32_e32 v4, v96
	v_mov_b32_e32 v5, v97
	v_mov_b32_e32 v6, v98
	v_mov_b32_e32 v7, v99
	v_mov_b32_e32 v8, v100
	v_mov_b32_e32 v9, v101
	v_mov_b32_e32 v10, v102
	v_mov_b32_e32 v11, v103
	v_mad_u64_u32 v[12:13], s[46:47], v3, s3, v[118:119]
	v_cvt_pk_bf16_f32 v4, v4, v5
	v_cvt_pk_bf16_f32 v5, v6, v7
	v_cvt_pk_bf16_f32 v6, v8, v9
	v_cvt_pk_bf16_f32 v7, v10, v11
	ds_write_b128 v12, v[4:7]
	v_add_u32_e32 v2, 0x600, v119
	v_mov_b32_e32 v3, s91
	v_mov_b32_e32 v4, s89
	v_lshlrev_b32_e32 v8, 5, v2
	v_cmp_gt_u32_e32 vcc, s81, v2
	v_mov_b32_e32 v6, s90
	v_mov_b32_e32 v7, s88
	v_cndmask_b32_e32 v5, v3, v4, vcc
	v_and_b32_e32 v3, 0xfe00, v8
	v_cndmask_b32_e32 v4, v6, v7, vcc
	v_lshl_or_b32 v114, s42, 2, v3
	v_mov_b32_e32 v121, v115
	v_lshl_add_u64 v[4:5], v[4:5], 0, v[114:115]
	v_lshl_add_u64 v[4:5], v[4:5], 0, v[120:121]
	v_lshl_add_u64 v[8:9], v[4:5], 0, s[66:67]
	v_add_co_u32_e32 v4, vcc, s82, v4
	v_lshrrev_b32_e32 v3, 4, v2
	s_nop 0
	v_addc_co_u32_e32 v5, vcc, 0, v5, vcc
	s_waitcnt vmcnt(8)
	v_mov_b32_e32 v4, v104
	v_mov_b32_e32 v5, v105
	v_mov_b32_e32 v6, v106
	v_mov_b32_e32 v7, v107
	v_mov_b32_e32 v8, v108
	v_mov_b32_e32 v9, v109
	v_mov_b32_e32 v10, v110
	v_mov_b32_e32 v11, v111
	v_mad_u64_u32 v[12:13], s[46:47], v3, s3, v[118:119]
	v_cvt_pk_bf16_f32 v4, v4, v5
	v_cvt_pk_bf16_f32 v5, v6, v7
	v_cvt_pk_bf16_f32 v6, v8, v9
	v_cvt_pk_bf16_f32 v7, v10, v11
	ds_write_b128 v12, v[4:7]
	v_add_u32_e32 v2, 0x800, v119
	v_mov_b32_e32 v3, s91
	v_mov_b32_e32 v4, s89
	v_lshlrev_b32_e32 v8, 5, v2
	v_cmp_gt_u32_e32 vcc, s81, v2
	v_mov_b32_e32 v6, s90
	v_mov_b32_e32 v7, s88
	v_cndmask_b32_e32 v5, v3, v4, vcc
	v_and_b32_e32 v3, 0xfe00, v8
	v_cndmask_b32_e32 v4, v6, v7, vcc
	v_lshl_or_b32 v114, s42, 2, v3
	v_mov_b32_e32 v121, v115
	v_lshl_add_u64 v[4:5], v[4:5], 0, v[114:115]
	v_lshl_add_u64 v[4:5], v[4:5], 0, v[120:121]
	v_lshl_add_u64 v[8:9], v[4:5], 0, s[66:67]
	v_add_co_u32_e32 v4, vcc, s82, v4
	v_lshrrev_b32_e32 v3, 4, v2
	s_nop 0
	v_addc_co_u32_e32 v5, vcc, 0, v5, vcc
	s_waitcnt vmcnt(6)
	v_mov_b32_e32 v4, v148
	v_mov_b32_e32 v5, v149
	v_mov_b32_e32 v6, v150
	v_mov_b32_e32 v7, v151
	v_mov_b32_e32 v8, v152
	v_mov_b32_e32 v9, v153
	v_mov_b32_e32 v10, v154
	v_mov_b32_e32 v11, v155
	v_mad_u64_u32 v[12:13], s[46:47], v3, s3, v[118:119]
	v_cvt_pk_bf16_f32 v4, v4, v5
	v_cvt_pk_bf16_f32 v5, v6, v7
	v_cvt_pk_bf16_f32 v6, v8, v9
	v_cvt_pk_bf16_f32 v7, v10, v11
	ds_write_b128 v12, v[4:7]
	v_add_u32_e32 v2, 0xa00, v119
	v_mov_b32_e32 v3, s91
	v_mov_b32_e32 v4, s89
	v_lshlrev_b32_e32 v8, 5, v2
	v_cmp_gt_u32_e32 vcc, s81, v2
	v_mov_b32_e32 v6, s90
	v_mov_b32_e32 v7, s88
	v_cndmask_b32_e32 v5, v3, v4, vcc
	v_and_b32_e32 v3, 0xfe00, v8
	v_cndmask_b32_e32 v4, v6, v7, vcc
	v_lshl_or_b32 v114, s42, 2, v3
	v_mov_b32_e32 v121, v115
	v_lshl_add_u64 v[4:5], v[4:5], 0, v[114:115]
	v_lshl_add_u64 v[4:5], v[4:5], 0, v[120:121]
	v_lshl_add_u64 v[8:9], v[4:5], 0, s[66:67]
	v_add_co_u32_e32 v4, vcc, s82, v4
	v_lshrrev_b32_e32 v3, 4, v2
	s_nop 0
	v_addc_co_u32_e32 v5, vcc, 0, v5, vcc
	s_waitcnt vmcnt(4)
	v_mov_b32_e32 v4, v156
	v_mov_b32_e32 v5, v157
	v_mov_b32_e32 v6, v158
	v_mov_b32_e32 v7, v159
	v_mov_b32_e32 v8, v160
	v_mov_b32_e32 v9, v161
	v_mov_b32_e32 v10, v162
	v_mov_b32_e32 v11, v163
	v_mad_u64_u32 v[12:13], s[46:47], v3, s3, v[118:119]
	v_cvt_pk_bf16_f32 v4, v4, v5
	v_cvt_pk_bf16_f32 v5, v6, v7
	v_cvt_pk_bf16_f32 v6, v8, v9
	v_cvt_pk_bf16_f32 v7, v10, v11
	ds_write_b128 v12, v[4:7]
	v_add_u32_e32 v2, 0xc00, v119
	v_mov_b32_e32 v3, s91
	v_mov_b32_e32 v4, s89
	v_lshlrev_b32_e32 v8, 5, v2
	v_cmp_gt_u32_e32 vcc, s81, v2
	v_mov_b32_e32 v6, s90
	v_mov_b32_e32 v7, s88
	v_cndmask_b32_e32 v5, v3, v4, vcc
	v_and_b32_e32 v3, 0xfe00, v8
	v_cndmask_b32_e32 v4, v6, v7, vcc
	v_lshl_or_b32 v114, s42, 2, v3
	v_mov_b32_e32 v121, v115
	v_lshl_add_u64 v[4:5], v[4:5], 0, v[114:115]
	v_lshl_add_u64 v[4:5], v[4:5], 0, v[120:121]
	v_lshl_add_u64 v[8:9], v[4:5], 0, s[66:67]
	v_add_co_u32_e32 v4, vcc, s82, v4
	v_lshrrev_b32_e32 v3, 4, v2
	s_nop 0
	v_addc_co_u32_e32 v5, vcc, 0, v5, vcc
	s_waitcnt vmcnt(2)
	v_mov_b32_e32 v4, v164
	v_mov_b32_e32 v5, v165
	v_mov_b32_e32 v6, v166
	v_mov_b32_e32 v7, v167
	v_mov_b32_e32 v8, v168
	v_mov_b32_e32 v9, v169
	v_mov_b32_e32 v10, v170
	v_mov_b32_e32 v11, v171
	v_mad_u64_u32 v[12:13], s[46:47], v3, s3, v[118:119]
	v_cvt_pk_bf16_f32 v4, v4, v5
	v_cvt_pk_bf16_f32 v5, v6, v7
	v_cvt_pk_bf16_f32 v6, v8, v9
	v_cvt_pk_bf16_f32 v7, v10, v11
	ds_write_b128 v12, v[4:7]
	v_add_u32_e32 v2, 0xe00, v119
	v_mov_b32_e32 v3, s91
	v_mov_b32_e32 v4, s89
	v_lshlrev_b32_e32 v8, 5, v2
	v_cmp_gt_u32_e32 vcc, s81, v2
	v_mov_b32_e32 v6, s90
	v_mov_b32_e32 v7, s88
	v_cndmask_b32_e32 v5, v3, v4, vcc
	v_and_b32_e32 v3, 0xfe00, v8
	v_cndmask_b32_e32 v4, v6, v7, vcc
	v_lshl_or_b32 v114, s42, 2, v3
	v_mov_b32_e32 v121, v115
	v_lshl_add_u64 v[4:5], v[4:5], 0, v[114:115]
	v_lshl_add_u64 v[4:5], v[4:5], 0, v[120:121]
	v_lshl_add_u64 v[8:9], v[4:5], 0, s[66:67]
	v_add_co_u32_e32 v4, vcc, s82, v4
	v_lshrrev_b32_e32 v3, 4, v2
	s_nop 0
	v_addc_co_u32_e32 v5, vcc, 0, v5, vcc
	s_waitcnt vmcnt(0)
	v_mov_b32_e32 v4, v172
	v_mov_b32_e32 v5, v173
	v_mov_b32_e32 v6, v174
	v_mov_b32_e32 v7, v175
	v_mov_b32_e32 v8, v176
	v_mov_b32_e32 v9, v177
	v_mov_b32_e32 v10, v178
	v_mov_b32_e32 v11, v179
	v_mad_u64_u32 v[12:13], s[46:47], v3, s3, v[118:119]
	v_cvt_pk_bf16_f32 v4, v4, v5
	v_cvt_pk_bf16_f32 v5, v6, v7
	v_cvt_pk_bf16_f32 v6, v8, v9
	v_cvt_pk_bf16_f32 v7, v10, v11
	ds_write_b128 v12, v[4:7]
